# speedup vs baseline: 1.0222x; 1.0073x over previous
; #define PG8_STAGE(bufoff, gbase, voff) do { _Pragma("unroll") for (int _i = 0; _i < 2; ++_i) \
;         __builtin_amdgcn_global_load_lds((const unsigned*)((const char*)(gbase) + (voff)[_i]), (PG8_LAS unsigned*)(lds + (bufoff) + ldsw + _i * 8192), 16, 0, 0); } while (0)
; #define PG8_LDA(dst, b, h) do { _Pragma("unroll") for (int m = 0; m < 4; ++m) _Pragma("unroll") for (int k = 0; k < 2; ++k) dst[m][k] = *(const PG8_LAS bf16x8*)(lds + PG8_SA(b, h) + aoff + m * 2048 + k * 1024); } while (0)
; #define PG8_LDB(dst, b, h) do { _Pragma("unroll") for (int n = 0; n < 2; ++n) _Pragma("unroll") for (int k = 0; k < 2; ++k) dst[n][k] = *(const PG8_LAS bf16x8*)(lds + PG8_SB(b, h) + boff + n * 2048 + k * 1024); } while (0)
; #define PG8_MMA(ai, bj, At, Bt) do { __builtin_amdgcn_s_setprio(1); _Pragma("unroll") for (int m = 0; m < 4; ++m) _Pragma("unroll") for (int n = 0; n < 2; ++n) _Pragma("unroll") for (int k = 0; k < 2; ++k) \
;         acc[ai][bj][m][n] = __builtin_amdgcn_mfma_f32_16x16x32_bf16(Bt[n][k], At[m][k], acc[ai][bj][m][n], 0, 0, 0); __builtin_amdgcn_s_setprio(0); } while (0)
; #define PG8_WAIT_V(n) asm volatile("s_waitcnt vmcnt(" #n ")" ::: "memory")
; #define PG8_WAIT_L(n) asm volatile("s_waitcnt lgkmcnt(" #n ")" ::: "memory")
; template <class Epi, class Sched, bool ALIGN_EPI = false, bool SP2 = false>
; __device__ __forceinline__ void gemm_phase(PG8_LAS unsigned char* lds, const Gemm g, const Sched& S, const Epi& E, const int wv) {
;     ...
;             const bool last = (t == nt - 2);
;             const char* a1 = cA + (size_t)(t + 1) * kstep;
;             const char* a2 = last ? nA : cA + (size_t)(t + 2) * kstep; const char* b2 = last ? nB : cB + (size_t)(t + 2) * kstep;
;             const char* a3 = a2 + kstep; const char* b3 = b2 + kstep;
;             if (last && has_next) S.a_ready(nxt);
;             if constexpr (SP2) {
;             PG8_LDB(B0, 0, 0); PG8_LDB(B1, 0, 1); PG8_SCHED; PG8_LDA(At, 0, 0); PG8_STAGE(PG8_SA(1, 1), a1 + hstep, voffA);
;             PG8_WAIT_V(8); PG8_WAIT_L(0); PG8_BAR; PG8_MMA(0, 0, At, B0); PG8_MMA(0, 1, At, B1); PG8_BAR; PG8_SCHED;
;             PG8_LDA(At, 0, 1); PG8_STAGE(PG8_SB(0, 0), b2, voffB); PG8_STAGE(PG8_SB(0, 1), b2 + hstep, voffB); PG8_STAGE(PG8_SA(0, 0), a2, voffA);
;             PG8_WAIT_V(8); PG8_WAIT_L(0); PG8_BAR; PG8_MMA(1, 0, At, B0); PG8_MMA(1, 1, At, B1); PG8_BAR; PG8_SCHED;
.LBB0_134:
	s_add_u32 s26, s24, 0xfffc0080
	s_addc_u32 s27, s25, -1
	s_add_i32 s51, 0, 0x10000
	s_cmp_eq_u32 s50, 12
	s_cselect_b32 s29, s17, s27
	s_cselect_b32 s28, s23, s26
	v_add_u32_e32 v0, s51, v183
	s_cselect_b32 s27, s15, s49
	s_cselect_b32 s26, s33, s48
	s_add_i32 s54, 0, 0x14000
	ds_read_b128 v[142:145], v0
	ds_read_b128 v[146:149], v0 offset:1024
	ds_read_b128 v[150:153], v0 offset:2048
	ds_read_b128 v[154:157], v0 offset:3072
	v_add_u32_e32 v0, s54, v183
	ds_read_b128 v[158:161], v0
	ds_read_b128 v[162:165], v0 offset:1024
	ds_read_b128 v[166:169], v0 offset:2048
	ds_read_b128 v[170:173], v0 offset:3072
	v_lshl_add_u64 v[208:209], s[24:25], 0, v[138:139]
	s_add_i32 m0, s39, 0xc000
	ds_read_b128 v[174:177], v186
	ds_read_b128 v[178:181], v186 offset:1024
	ds_read_b128 v[188:191], v186 offset:2048
	ds_read_b128 v[192:195], v186 offset:3072
	ds_read_b128 v[196:199], v186 offset:4096
	ds_read_b128 v[200:203], v186 offset:5120
	ds_read_b128 v[204:207], v186 offset:6144
	ds_read_b128 v[218:221], v186 offset:7168
	global_load_lds_dwordx4 v[208:209], off
	v_lshl_add_u64 v[208:209], s[24:25], 0, v[140:141]
	s_add_i32 m0, s39, 0xe000
	s_nop 0
	global_load_lds_dwordx4 v[208:209], off
	s_waitcnt vmcnt(8)
	s_waitcnt lgkmcnt(0)
	s_setprio 1
	s_barrier
	s_waitcnt lgkmcnt(0)
	v_mfma_f32_16x16x32_bf16 v[126:129], v[142:145], v[174:177], v[126:129]
	v_mfma_f32_16x16x32_bf16 v[122:125], v[150:153], v[174:177], v[122:125]
	v_mfma_f32_16x16x32_bf16 v[110:113], v[142:145], v[188:191], v[110:113]
	v_mfma_f32_16x16x32_bf16 v[106:109], v[150:153], v[188:191], v[106:109]
	v_mfma_f32_16x16x32_bf16 v[94:97], v[142:145], v[196:199], v[94:97]
	v_mfma_f32_16x16x32_bf16 v[90:93], v[150:153], v[196:199], v[90:93]
	v_mfma_f32_16x16x32_bf16 v[78:81], v[142:145], v[204:207], v[78:81]
	v_mfma_f32_16x16x32_bf16 v[74:77], v[150:153], v[204:207], v[74:77]
	v_mfma_f32_16x16x32_bf16 v[126:129], v[146:149], v[178:181], v[126:129]
	v_mfma_f32_16x16x32_bf16 v[122:125], v[154:157], v[178:181], v[122:125]
	v_mfma_f32_16x16x32_bf16 v[110:113], v[146:149], v[192:195], v[110:113]
	v_mfma_f32_16x16x32_bf16 v[106:109], v[154:157], v[192:195], v[106:109]
	v_mfma_f32_16x16x32_bf16 v[94:97], v[146:149], v[200:203], v[94:97]
	v_mfma_f32_16x16x32_bf16 v[90:93], v[154:157], v[200:203], v[90:93]
	v_mfma_f32_16x16x32_bf16 v[78:81], v[146:149], v[218:221], v[78:81]
	v_mfma_f32_16x16x32_bf16 v[74:77], v[154:157], v[218:221], v[74:77]
	s_setprio 0
	s_setprio 1
	v_mfma_f32_16x16x32_bf16 v[118:121], v[158:161], v[174:177], v[118:121]
	v_mfma_f32_16x16x32_bf16 v[114:117], v[166:169], v[174:177], v[114:117]
	v_mfma_f32_16x16x32_bf16 v[102:105], v[158:161], v[188:191], v[102:105]
	v_mfma_f32_16x16x32_bf16 v[98:101], v[166:169], v[188:191], v[98:101]
	v_mfma_f32_16x16x32_bf16 v[86:89], v[158:161], v[196:199], v[86:89]
	v_mfma_f32_16x16x32_bf16 v[82:85], v[166:169], v[196:199], v[82:85]
	v_mfma_f32_16x16x32_bf16 v[70:73], v[158:161], v[204:207], v[70:73]
	v_mfma_f32_16x16x32_bf16 v[66:69], v[166:169], v[204:207], v[66:69]
	v_mfma_f32_16x16x32_bf16 v[118:121], v[162:165], v[178:181], v[118:121]
	v_mfma_f32_16x16x32_bf16 v[114:117], v[170:173], v[178:181], v[114:117]
	v_mfma_f32_16x16x32_bf16 v[102:105], v[162:165], v[192:195], v[102:105]
	v_mfma_f32_16x16x32_bf16 v[98:101], v[170:173], v[192:195], v[98:101]
	v_mfma_f32_16x16x32_bf16 v[86:89], v[162:165], v[200:203], v[86:89]
	v_mfma_f32_16x16x32_bf16 v[82:85], v[170:173], v[200:203], v[82:85]
	v_mfma_f32_16x16x32_bf16 v[70:73], v[162:165], v[218:221], v[70:73]
	v_mfma_f32_16x16x32_bf16 v[66:69], v[170:173], v[218:221], v[66:69]
	s_barrier
	s_setprio 0
	s_add_i32 s51, s51, s35
	v_lshl_add_u64 v[208:209], s[26:27], 0, v[134:135]
	s_mov_b32 m0, s51
	ds_read_b128 v[174:177], v186 offset:16384
	ds_read_b128 v[178:181], v186 offset:17408
	ds_read_b128 v[188:191], v186 offset:18432
	ds_read_b128 v[192:195], v186 offset:19456
	ds_read_b128 v[196:199], v186 offset:20480
	ds_read_b128 v[200:203], v186 offset:21504
	ds_read_b128 v[204:207], v186 offset:22528
	ds_read_b128 v[218:221], v186 offset:23552
	global_load_lds_dwordx4 v[208:209], off
	s_add_i32 m0, s51, 0x2000
	s_add_u32 s52, s26, 0x40000
	v_lshl_add_u64 v[210:211], s[26:27], 0, v[130:131]
	s_addc_u32 s53, s27, 0
	s_add_i32 s51, s54, s35
	global_load_lds_dwordx4 v[210:211], off
	v_lshl_add_u64 v[212:213], s[52:53], 0, v[134:135]
	s_mov_b32 m0, s51
	v_lshl_add_u64 v[214:215], s[28:29], 0, v[132:133]
	global_load_lds_dwordx4 v[212:213], off
	v_lshl_add_u64 v[212:213], s[52:53], 0, v[130:131]
	s_add_i32 m0, s51, 0x2000
	s_nop 0
	global_load_lds_dwordx4 v[212:213], off
	v_lshl_add_u64 v[212:213], s[28:29], 0, v[136:137]
	s_mov_b32 m0, s39
	s_nop 0
	global_load_lds_dwordx4 v[212:213], off
	s_mov_b32 m0, s40
	s_nop 0
	global_load_lds_dwordx4 v[214:215], off
	s_waitcnt vmcnt(8)
	s_waitcnt lgkmcnt(0)
	s_setprio 1
	s_barrier
; #define PG8_STAGE(bufoff, gbase, voff) do { _Pragma("unroll") for (int _i = 0; _i < 2; ++_i) \
;         __builtin_amdgcn_global_load_lds((const unsigned*)((const char*)(gbase) + (voff)[_i]), (PG8_LAS unsigned*)(lds + (bufoff) + ldsw + _i * 8192), 16, 0, 0); } while (0)
; #define PG8_LDA(dst, b, h) do { _Pragma("unroll") for (int m = 0; m < 4; ++m) _Pragma("unroll") for (int k = 0; k < 2; ++k) dst[m][k] = *(const PG8_LAS bf16x8*)(lds + PG8_SA(b, h) + aoff + m * 2048 + k * 1024); } while (0)
; #define PG8_LDB(dst, b, h) do { _Pragma("unroll") for (int n = 0; n < 2; ++n) _Pragma("unroll") for (int k = 0; k < 2; ++k) dst[n][k] = *(const PG8_LAS bf16x8*)(lds + PG8_SB(b, h) + boff + n * 2048 + k * 1024); } while (0)
; #define PG8_MMA(ai, bj, At, Bt) do { __builtin_amdgcn_s_setprio(1); _Pragma("unroll") for (int m = 0; m < 4; ++m) _Pragma("unroll") for (int n = 0; n < 2; ++n) _Pragma("unroll") for (int k = 0; k < 2; ++k) \
;         acc[ai][bj][m][n] = __builtin_amdgcn_mfma_f32_16x16x32_bf16(Bt[n][k], At[m][k], acc[ai][bj][m][n], 0, 0, 0); __builtin_amdgcn_s_setprio(0); } while (0)
; #define PG8_WAIT_V(n) asm volatile("s_waitcnt vmcnt(" #n ")" ::: "memory")
; #define PG8_WAIT_L(n) asm volatile("s_waitcnt lgkmcnt(" #n ")" ::: "memory")
; #define PG8_BAR __builtin_amdgcn_s_barrier()
; #define PG8_SCHED __builtin_amdgcn_sched_barrier(0)
; template <class Epi, class Sched, bool ALIGN_EPI = false, bool SP2 = false>
; __device__ __forceinline__ void gemm_phase(PG8_LAS unsigned char* lds, const Gemm g, const Sched& S, const Epi& E, const int wv) {
;     ...
;             PG8_WAIT_V(8); PG8_WAIT_L(0); PG8_BAR; PG8_MMA(1, 0, At, B0); PG8_MMA(1, 1, At, B1); PG8_BAR; PG8_SCHED;
;             PG8_LDB(B0, 1, 0); PG8_LDB(B1, 1, 1); PG8_SCHED; PG8_LDA(At, 1, 0); PG8_STAGE(PG8_SA(0, 1), a2 + hstep, voffA);
;             PG8_WAIT_V(8); PG8_WAIT_L(0); PG8_BAR; PG8_MMA(0, 0, At, B0); PG8_MMA(0, 1, At, B1); PG8_BAR; PG8_SCHED;
	s_waitcnt lgkmcnt(0)
	v_mfma_f32_16x16x32_bf16 v[62:65], v[142:145], v[174:177], v[62:65]
	v_mfma_f32_16x16x32_bf16 v[58:61], v[150:153], v[174:177], v[58:61]
	v_mfma_f32_16x16x32_bf16 v[46:49], v[142:145], v[188:191], v[46:49]
	v_mfma_f32_16x16x32_bf16 v[42:45], v[150:153], v[188:191], v[42:45]
	v_mfma_f32_16x16x32_bf16 v[30:33], v[142:145], v[196:199], v[30:33]
	v_mfma_f32_16x16x32_bf16 v[26:29], v[150:153], v[196:199], v[26:29]
	v_mfma_f32_16x16x32_bf16 v[14:17], v[142:145], v[204:207], v[14:17]
	v_mfma_f32_16x16x32_bf16 v[10:13], v[150:153], v[204:207], v[10:13]
	v_mfma_f32_16x16x32_bf16 v[62:65], v[146:149], v[178:181], v[62:65]
	v_mfma_f32_16x16x32_bf16 v[58:61], v[154:157], v[178:181], v[58:61]
	v_mfma_f32_16x16x32_bf16 v[46:49], v[146:149], v[192:195], v[46:49]
	v_mfma_f32_16x16x32_bf16 v[42:45], v[154:157], v[192:195], v[42:45]
	v_mfma_f32_16x16x32_bf16 v[30:33], v[146:149], v[200:203], v[30:33]
	v_mfma_f32_16x16x32_bf16 v[26:29], v[154:157], v[200:203], v[26:29]
	v_mfma_f32_16x16x32_bf16 v[14:17], v[146:149], v[218:221], v[14:17]
	v_mfma_f32_16x16x32_bf16 v[10:13], v[154:157], v[218:221], v[10:13]
	s_setprio 0
	s_setprio 1
	v_mfma_f32_16x16x32_bf16 v[54:57], v[158:161], v[174:177], v[54:57]
	v_mfma_f32_16x16x32_bf16 v[50:53], v[166:169], v[174:177], v[50:53]
	v_mfma_f32_16x16x32_bf16 v[38:41], v[158:161], v[188:191], v[38:41]
	v_mfma_f32_16x16x32_bf16 v[34:37], v[166:169], v[188:191], v[34:37]
	v_mfma_f32_16x16x32_bf16 v[22:25], v[158:161], v[196:199], v[22:25]
	v_mfma_f32_16x16x32_bf16 v[18:21], v[166:169], v[196:199], v[18:21]
	v_mfma_f32_16x16x32_bf16 v[6:9], v[158:161], v[204:207], v[6:9]
	v_mfma_f32_16x16x32_bf16 v[2:5], v[166:169], v[204:207], v[2:5]
	v_mfma_f32_16x16x32_bf16 v[54:57], v[162:165], v[178:181], v[54:57]
	v_mfma_f32_16x16x32_bf16 v[50:53], v[170:173], v[178:181], v[50:53]
	v_mfma_f32_16x16x32_bf16 v[38:41], v[162:165], v[192:195], v[38:41]
	v_mfma_f32_16x16x32_bf16 v[34:37], v[170:173], v[192:195], v[34:37]
	v_mfma_f32_16x16x32_bf16 v[22:25], v[162:165], v[200:203], v[22:25]
	v_mfma_f32_16x16x32_bf16 v[18:21], v[170:173], v[200:203], v[18:21]
	v_mfma_f32_16x16x32_bf16 v[6:9], v[162:165], v[218:221], v[6:9]
	v_mfma_f32_16x16x32_bf16 v[2:5], v[170:173], v[218:221], v[2:5]
	s_barrier
	s_setprio 0
	s_add_i32 s51, 0, 0x18000
	v_add_u32_e32 v0, s51, v183
	s_add_i32 s52, 0, 0x1c000
	ds_read_b128 v[142:145], v0
	ds_read_b128 v[146:149], v0 offset:1024
	ds_read_b128 v[150:153], v0 offset:2048
	ds_read_b128 v[154:157], v0 offset:3072
	v_add_u32_e32 v0, s52, v183
	ds_read_b128 v[158:161], v0
	ds_read_b128 v[162:165], v0 offset:1024
	ds_read_b128 v[166:169], v0 offset:2048
	ds_read_b128 v[170:173], v0 offset:3072
	s_add_u32 s28, s28, 0x40000
	s_addc_u32 s29, s29, 0
	s_mov_b32 m0, s41
	v_lshl_add_u64 v[216:217], s[28:29], 0, v[136:137]
	ds_read_b128 v[174:177], v186 offset:32768
	ds_read_b128 v[178:181], v186 offset:33792
	ds_read_b128 v[188:191], v186 offset:34816
	ds_read_b128 v[192:195], v186 offset:35840
	ds_read_b128 v[196:199], v186 offset:36864
	ds_read_b128 v[200:203], v186 offset:37888
	ds_read_b128 v[204:207], v186 offset:38912
	ds_read_b128 v[218:221], v186 offset:39936
	global_load_lds_dwordx4 v[216:217], off
	v_lshl_add_u64 v[216:217], s[28:29], 0, v[132:133]
	s_mov_b32 m0, s42
	s_nop 0
	global_load_lds_dwordx4 v[216:217], off
	s_waitcnt vmcnt(8)
	s_waitcnt lgkmcnt(0)
	s_setprio 1
	s_barrier
	s_waitcnt lgkmcnt(0)
	v_mfma_f32_16x16x32_bf16 v[126:129], v[142:145], v[174:177], v[126:129]
	v_mfma_f32_16x16x32_bf16 v[122:125], v[150:153], v[174:177], v[122:125]
	v_mfma_f32_16x16x32_bf16 v[110:113], v[142:145], v[188:191], v[110:113]
	v_mfma_f32_16x16x32_bf16 v[106:109], v[150:153], v[188:191], v[106:109]
	v_mfma_f32_16x16x32_bf16 v[94:97], v[142:145], v[196:199], v[94:97]
	v_mfma_f32_16x16x32_bf16 v[90:93], v[150:153], v[196:199], v[90:93]
	v_mfma_f32_16x16x32_bf16 v[78:81], v[142:145], v[204:207], v[78:81]
	v_mfma_f32_16x16x32_bf16 v[74:77], v[150:153], v[204:207], v[74:77]
	v_mfma_f32_16x16x32_bf16 v[126:129], v[146:149], v[178:181], v[126:129]
	v_mfma_f32_16x16x32_bf16 v[122:125], v[154:157], v[178:181], v[122:125]
	v_mfma_f32_16x16x32_bf16 v[110:113], v[146:149], v[192:195], v[110:113]
	v_mfma_f32_16x16x32_bf16 v[106:109], v[154:157], v[192:195], v[106:109]
	v_mfma_f32_16x16x32_bf16 v[94:97], v[146:149], v[200:203], v[94:97]
	v_mfma_f32_16x16x32_bf16 v[90:93], v[154:157], v[200:203], v[90:93]
	v_mfma_f32_16x16x32_bf16 v[78:81], v[146:149], v[218:221], v[78:81]
	v_mfma_f32_16x16x32_bf16 v[74:77], v[154:157], v[218:221], v[74:77]
	s_setprio 0
	s_setprio 1
	v_mfma_f32_16x16x32_bf16 v[118:121], v[158:161], v[174:177], v[118:121]
	v_mfma_f32_16x16x32_bf16 v[114:117], v[166:169], v[174:177], v[114:117]
	v_mfma_f32_16x16x32_bf16 v[102:105], v[158:161], v[188:191], v[102:105]
	v_mfma_f32_16x16x32_bf16 v[98:101], v[166:169], v[188:191], v[98:101]
	v_mfma_f32_16x16x32_bf16 v[86:89], v[158:161], v[196:199], v[86:89]
	v_mfma_f32_16x16x32_bf16 v[82:85], v[166:169], v[196:199], v[82:85]
	v_mfma_f32_16x16x32_bf16 v[70:73], v[158:161], v[204:207], v[70:73]
	v_mfma_f32_16x16x32_bf16 v[66:69], v[166:169], v[204:207], v[66:69]
	v_mfma_f32_16x16x32_bf16 v[118:121], v[162:165], v[178:181], v[118:121]
	v_mfma_f32_16x16x32_bf16 v[114:117], v[170:173], v[178:181], v[114:117]
	v_mfma_f32_16x16x32_bf16 v[102:105], v[162:165], v[192:195], v[102:105]
	v_mfma_f32_16x16x32_bf16 v[98:101], v[170:173], v[192:195], v[98:101]
	v_mfma_f32_16x16x32_bf16 v[86:89], v[162:165], v[200:203], v[86:89]
	v_mfma_f32_16x16x32_bf16 v[82:85], v[170:173], v[200:203], v[82:85]
	v_mfma_f32_16x16x32_bf16 v[70:73], v[162:165], v[218:221], v[70:73]
	v_mfma_f32_16x16x32_bf16 v[66:69], v[170:173], v[218:221], v[66:69]
	s_barrier
; #define PG8_STAGE(bufoff, gbase, voff) do { _Pragma("unroll") for (int _i = 0; _i < 2; ++_i) \
;         __builtin_amdgcn_global_load_lds((const unsigned*)((const char*)(gbase) + (voff)[_i]), (PG8_LAS unsigned*)(lds + (bufoff) + ldsw + _i * 8192), 16, 0, 0); } while (0)
; #define PG8_LDA(dst, b, h) do { _Pragma("unroll") for (int m = 0; m < 4; ++m) _Pragma("unroll") for (int k = 0; k < 2; ++k) dst[m][k] = *(const PG8_LAS bf16x8*)(lds + PG8_SA(b, h) + aoff + m * 2048 + k * 1024); } while (0)
; #define PG8_MMA(ai, bj, At, Bt) do { __builtin_amdgcn_s_setprio(1); _Pragma("unroll") for (int m = 0; m < 4; ++m) _Pragma("unroll") for (int n = 0; n < 2; ++n) _Pragma("unroll") for (int k = 0; k < 2; ++k) \
;         acc[ai][bj][m][n] = __builtin_amdgcn_mfma_f32_16x16x32_bf16(Bt[n][k], At[m][k], acc[ai][bj][m][n], 0, 0, 0); __builtin_amdgcn_s_setprio(0); } while (0)
; #define PG8_WAIT_V(n) asm volatile("s_waitcnt vmcnt(" #n ")" ::: "memory")
; #define PG8_WAIT_L(n) asm volatile("s_waitcnt lgkmcnt(" #n ")" ::: "memory")
; #define PG8_BAR __builtin_amdgcn_s_barrier()
; #define PG8_SCHED __builtin_amdgcn_sched_barrier(0)
; template <class Epi, class Sched, bool ALIGN_EPI = false, bool SP2 = false>
; __device__ __forceinline__ void gemm_phase(PG8_LAS unsigned char* lds, const Gemm g, const Sched& S, const Epi& E, const int wv) {
;     ...
;             PG8_LDA(At, 1, 1); PG8_STAGE(PG8_SB(1, 0), b3, voffB); PG8_STAGE(PG8_SB(1, 1), b3 + hstep, voffB); PG8_STAGE(PG8_SA(1, 0), a3, voffA);
;             PG8_WAIT_V(8); PG8_WAIT_L(0); PG8_BAR; PG8_MMA(1, 0, At, B0); PG8_MMA(1, 1, At, B1); PG8_BAR; PG8_SCHED;
;     ...
;         if constexpr (ALIGN_EPI) { if (wr == 0) PG8_BAR; }
	s_setprio 0
	s_add_i32 s28, s51, s35
	v_lshl_add_u64 v[208:209], v[208:209], 0, s[2:3]
	s_mov_b32 m0, s28
	ds_read_b128 v[174:177], v186 offset:49152
	ds_read_b128 v[178:181], v186 offset:50176
	ds_read_b128 v[188:191], v186 offset:51200
	ds_read_b128 v[192:195], v186 offset:52224
	ds_read_b128 v[196:199], v186 offset:53248
	ds_read_b128 v[200:203], v186 offset:54272
	ds_read_b128 v[204:207], v186 offset:55296
	ds_read_b128 v[218:221], v186 offset:56320
	global_load_lds_dwordx4 v[208:209], off
	s_add_i32 m0, s28, 0x2000
	s_add_u32 s26, s26, 0x40080
	v_lshl_add_u64 v[208:209], v[210:211], 0, s[2:3]
	s_addc_u32 s27, s27, 0
	s_add_i32 s28, s52, s35
	global_load_lds_dwordx4 v[208:209], off
	v_lshl_add_u64 v[208:209], s[26:27], 0, v[134:135]
	s_mov_b32 m0, s28
	s_nop 0
	global_load_lds_dwordx4 v[208:209], off
	v_lshl_add_u64 v[208:209], s[26:27], 0, v[130:131]
	s_add_i32 m0, s28, 0x2000
	s_nop 0
	global_load_lds_dwordx4 v[208:209], off
	v_lshl_add_u64 v[208:209], v[212:213], 0, s[2:3]
	s_mov_b32 m0, s44
	s_nop 0
	global_load_lds_dwordx4 v[208:209], off
	v_lshl_add_u64 v[208:209], v[214:215], 0, s[2:3]
	s_mov_b32 m0, s45
	s_nop 0
	global_load_lds_dwordx4 v[208:209], off
	s_waitcnt vmcnt(8)
	s_waitcnt lgkmcnt(0)
	s_setprio 1
	s_barrier
	s_waitcnt lgkmcnt(0)
	v_mfma_f32_16x16x32_bf16 v[62:65], v[142:145], v[174:177], v[62:65]
	v_mfma_f32_16x16x32_bf16 v[58:61], v[150:153], v[174:177], v[58:61]
	v_mfma_f32_16x16x32_bf16 v[46:49], v[142:145], v[188:191], v[46:49]
	v_mfma_f32_16x16x32_bf16 v[42:45], v[150:153], v[188:191], v[42:45]
	v_mfma_f32_16x16x32_bf16 v[30:33], v[142:145], v[196:199], v[30:33]
	v_mfma_f32_16x16x32_bf16 v[26:29], v[150:153], v[196:199], v[26:29]
	v_mfma_f32_16x16x32_bf16 v[14:17], v[142:145], v[204:207], v[14:17]
	v_mfma_f32_16x16x32_bf16 v[10:13], v[150:153], v[204:207], v[10:13]
	v_mfma_f32_16x16x32_bf16 v[62:65], v[146:149], v[178:181], v[62:65]
	v_mfma_f32_16x16x32_bf16 v[58:61], v[154:157], v[178:181], v[58:61]
	v_mfma_f32_16x16x32_bf16 v[46:49], v[146:149], v[192:195], v[46:49]
	v_mfma_f32_16x16x32_bf16 v[42:45], v[154:157], v[192:195], v[42:45]
	v_mfma_f32_16x16x32_bf16 v[30:33], v[146:149], v[200:203], v[30:33]
	v_mfma_f32_16x16x32_bf16 v[26:29], v[154:157], v[200:203], v[26:29]
	v_mfma_f32_16x16x32_bf16 v[14:17], v[146:149], v[218:221], v[14:17]
	v_mfma_f32_16x16x32_bf16 v[10:13], v[154:157], v[218:221], v[10:13]
	s_setprio 0
	s_setprio 1
	v_mfma_f32_16x16x32_bf16 v[54:57], v[158:161], v[174:177], v[54:57]
	v_mfma_f32_16x16x32_bf16 v[50:53], v[166:169], v[174:177], v[50:53]
	v_mfma_f32_16x16x32_bf16 v[38:41], v[158:161], v[188:191], v[38:41]
	v_mfma_f32_16x16x32_bf16 v[34:37], v[166:169], v[188:191], v[34:37]
	v_mfma_f32_16x16x32_bf16 v[22:25], v[158:161], v[196:199], v[22:25]
	v_mfma_f32_16x16x32_bf16 v[18:21], v[166:169], v[196:199], v[18:21]
	v_mfma_f32_16x16x32_bf16 v[6:9], v[158:161], v[204:207], v[6:9]
	v_mfma_f32_16x16x32_bf16 v[2:5], v[166:169], v[204:207], v[2:5]
	v_mfma_f32_16x16x32_bf16 v[54:57], v[162:165], v[178:181], v[54:57]
	v_mfma_f32_16x16x32_bf16 v[50:53], v[170:173], v[178:181], v[50:53]
	v_mfma_f32_16x16x32_bf16 v[38:41], v[162:165], v[192:195], v[38:41]
	v_mfma_f32_16x16x32_bf16 v[34:37], v[170:173], v[192:195], v[34:37]
	v_mfma_f32_16x16x32_bf16 v[22:25], v[162:165], v[200:203], v[22:25]
	v_mfma_f32_16x16x32_bf16 v[18:21], v[170:173], v[200:203], v[18:21]
	v_mfma_f32_16x16x32_bf16 v[6:9], v[162:165], v[218:221], v[6:9]
	v_mfma_f32_16x16x32_bf16 v[2:5], v[170:173], v[218:221], v[2:5]
	s_barrier
	s_setprio 0
	s_add_i32 s50, s50, 2
	s_add_u32 s24, s24, 0x100
	s_addc_u32 s25, s25, 0
	s_add_u32 s48, s48, 0x100
	s_addc_u32 s49, s49, 0
	s_cmp_gt_u32 s50, 13
	s_cbranch_scc0 .LBB0_134
	s_and_b64 vcc, exec, s[10:11]
	s_cbranch_vccz .LBB0_137
	s_barrier

; #define PG8_STAGE(bufoff, gbase, voff) do { _Pragma("unroll") for (int _i = 0; _i < 2; ++_i) \
;         __builtin_amdgcn_global_load_lds((const unsigned*)((const char*)(gbase) + (voff)[_i]), (PG8_LAS unsigned*)(lds + (bufoff) + ldsw + _i * 8192), 16, 0, 0); } while (0)
; #define PG8_LDA(dst, b, h) do { _Pragma("unroll") for (int m = 0; m < 4; ++m) _Pragma("unroll") for (int k = 0; k < 2; ++k) dst[m][k] = *(const PG8_LAS bf16x8*)(lds + PG8_SA(b, h) + aoff + m * 2048 + k * 1024); } while (0)
; #define PG8_LDB(dst, b, h) do { _Pragma("unroll") for (int n = 0; n < 2; ++n) _Pragma("unroll") for (int k = 0; k < 2; ++k) dst[n][k] = *(const PG8_LAS bf16x8*)(lds + PG8_SB(b, h) + boff + n * 2048 + k * 1024); } while (0)
; #define PG8_MMA(ai, bj, At, Bt) do { __builtin_amdgcn_s_setprio(1); _Pragma("unroll") for (int m = 0; m < 4; ++m) _Pragma("unroll") for (int n = 0; n < 2; ++n) _Pragma("unroll") for (int k = 0; k < 2; ++k) \
;         acc[ai][bj][m][n] = __builtin_amdgcn_mfma_f32_16x16x32_bf16(Bt[n][k], At[m][k], acc[ai][bj][m][n], 0, 0, 0); __builtin_amdgcn_s_setprio(0); } while (0)
; #define PG8_WAIT_V(n) asm volatile("s_waitcnt vmcnt(" #n ")" ::: "memory")
; #define PG8_WAIT_L(n) asm volatile("s_waitcnt lgkmcnt(" #n ")" ::: "memory")
; #define PG8_BAR __builtin_amdgcn_s_barrier()
; #define PG8_SCHED __builtin_amdgcn_sched_barrier(0)
; template <class Epi, class Sched, bool ALIGN_EPI = false, bool SP2 = false>
; __device__ __forceinline__ void gemm_phase(PG8_LAS unsigned char* lds, const Gemm g, const Sched& S, const Epi& E, const int wv) {
;     ...
;             const bool last = (t == nt - 2);
;             const char* a1 = cA + (size_t)(t + 1) * kstep;
;             const char* a2 = last ? nA : cA + (size_t)(t + 2) * kstep; const char* b2 = last ? nB : cB + (size_t)(t + 2) * kstep;
;             const char* a3 = a2 + kstep; const char* b3 = b2 + kstep;
;             if (last && has_next) S.a_ready(nxt);
;             if constexpr (SP2) {
;             PG8_LDB(B0, 0, 0); PG8_LDB(B1, 0, 1); PG8_SCHED; PG8_LDA(At, 0, 0); PG8_STAGE(PG8_SA(1, 1), a1 + hstep, voffA);
;             PG8_WAIT_V(8); PG8_WAIT_L(0); PG8_BAR; PG8_MMA(0, 0, At, B0); PG8_MMA(0, 1, At, B1); PG8_BAR; PG8_SCHED;
;             PG8_LDA(At, 0, 1); PG8_STAGE(PG8_SB(0, 0), b2, voffB); PG8_STAGE(PG8_SB(0, 1), b2 + hstep, voffB); PG8_STAGE(PG8_SA(0, 0), a2, voffA);
.LBB0_156:
	s_add_u32 s20, s18, 0xfffc0080
	s_addc_u32 s21, s19, -1
	s_add_i32 s45, 0, 0x10000
	s_cmp_eq_u32 s44, 12
	s_cselect_b32 s23, s11, s21
	s_cselect_b32 s22, s40, s20
	v_add_u32_e32 v152, s45, v155
	s_cselect_b32 s21, s9, s43
	s_cselect_b32 s20, s41, s42
	s_add_i32 s48, 0, 0x14000
	ds_read_b128 v[140:143], v152
	ds_read_b128 v[144:147], v152 offset:1024
	ds_read_b128 v[148:151], v152 offset:2048
	ds_read_b128 v[158:161], v152 offset:3072
	v_add_u32_e32 v152, s48, v155
	ds_read_b128 v[162:165], v152
	ds_read_b128 v[166:169], v152 offset:1024
	ds_read_b128 v[170:173], v152 offset:2048
	ds_read_b128 v[174:177], v152 offset:3072
	v_lshl_add_u64 v[152:153], s[18:19], 0, v[136:137]
	s_add_i32 m0, s17, 0xc000
	ds_read_b128 v[178:181], v157
	ds_read_b128 v[182:185], v157 offset:1024
	ds_read_b128 v[186:189], v157 offset:2048
	ds_read_b128 v[190:193], v157 offset:3072
	ds_read_b128 v[194:197], v157 offset:4096
	ds_read_b128 v[198:201], v157 offset:5120
	ds_read_b128 v[202:205], v157 offset:6144
	ds_read_b128 v[206:209], v157 offset:7168
	global_load_lds_dwordx4 v[152:153], off
	v_lshl_add_u64 v[152:153], s[18:19], 0, v[138:139]
	s_add_i32 m0, s17, 0xe000
	s_nop 0
	global_load_lds_dwordx4 v[152:153], off
	s_waitcnt vmcnt(8)
	s_waitcnt lgkmcnt(0)
	s_setprio 1
	s_barrier
	s_waitcnt lgkmcnt(0)
	v_mfma_f32_16x16x32_bf16 v[126:129], v[140:143], v[178:181], v[126:129]
	v_mfma_f32_16x16x32_bf16 v[122:125], v[148:151], v[178:181], v[122:125]
	v_mfma_f32_16x16x32_bf16 v[118:121], v[140:143], v[186:189], v[118:121]
	v_mfma_f32_16x16x32_bf16 v[114:117], v[148:151], v[186:189], v[114:117]
	v_mfma_f32_16x16x32_bf16 v[98:101], v[140:143], v[194:197], v[98:101]
	v_mfma_f32_16x16x32_bf16 v[90:93], v[148:151], v[194:197], v[90:93]
	v_mfma_f32_16x16x32_bf16 v[78:81], v[140:143], v[202:205], v[78:81]
	v_mfma_f32_16x16x32_bf16 v[74:77], v[148:151], v[202:205], v[74:77]
	v_mfma_f32_16x16x32_bf16 v[126:129], v[144:147], v[182:185], v[126:129]
	v_mfma_f32_16x16x32_bf16 v[122:125], v[158:161], v[182:185], v[122:125]
	v_mfma_f32_16x16x32_bf16 v[118:121], v[144:147], v[190:193], v[118:121]
	v_mfma_f32_16x16x32_bf16 v[114:117], v[158:161], v[190:193], v[114:117]
	v_mfma_f32_16x16x32_bf16 v[98:101], v[144:147], v[198:201], v[98:101]
	v_mfma_f32_16x16x32_bf16 v[90:93], v[158:161], v[198:201], v[90:93]
	v_mfma_f32_16x16x32_bf16 v[78:81], v[144:147], v[206:209], v[78:81]
	v_mfma_f32_16x16x32_bf16 v[74:77], v[158:161], v[206:209], v[74:77]
	s_setprio 0
	s_setprio 1
	v_mfma_f32_16x16x32_bf16 v[110:113], v[162:165], v[178:181], v[110:113]
	v_mfma_f32_16x16x32_bf16 v[106:109], v[170:173], v[178:181], v[106:109]
	v_mfma_f32_16x16x32_bf16 v[102:105], v[162:165], v[186:189], v[102:105]
	v_mfma_f32_16x16x32_bf16 v[94:97], v[170:173], v[186:189], v[94:97]
	v_mfma_f32_16x16x32_bf16 v[86:89], v[162:165], v[194:197], v[86:89]
	v_mfma_f32_16x16x32_bf16 v[82:85], v[170:173], v[194:197], v[82:85]
	v_mfma_f32_16x16x32_bf16 v[70:73], v[162:165], v[202:205], v[70:73]
	v_mfma_f32_16x16x32_bf16 v[66:69], v[170:173], v[202:205], v[66:69]
	v_mfma_f32_16x16x32_bf16 v[110:113], v[166:169], v[182:185], v[110:113]
	v_mfma_f32_16x16x32_bf16 v[106:109], v[174:177], v[182:185], v[106:109]
	v_mfma_f32_16x16x32_bf16 v[102:105], v[166:169], v[190:193], v[102:105]
	v_mfma_f32_16x16x32_bf16 v[94:97], v[174:177], v[190:193], v[94:97]
	v_mfma_f32_16x16x32_bf16 v[86:89], v[166:169], v[198:201], v[86:89]
	v_mfma_f32_16x16x32_bf16 v[82:85], v[174:177], v[198:201], v[82:85]
	v_mfma_f32_16x16x32_bf16 v[70:73], v[166:169], v[206:209], v[70:73]
	v_mfma_f32_16x16x32_bf16 v[66:69], v[174:177], v[206:209], v[66:69]
	s_barrier
	s_setprio 0
	s_add_i32 s45, s45, s24
	v_lshl_add_u64 v[152:153], s[20:21], 0, v[0:1]
	s_mov_b32 m0, s45
	ds_read_b128 v[178:181], v157 offset:16384
	ds_read_b128 v[182:185], v157 offset:17408
	ds_read_b128 v[186:189], v157 offset:18432
	ds_read_b128 v[190:193], v157 offset:19456
	ds_read_b128 v[194:197], v157 offset:20480
	ds_read_b128 v[198:201], v157 offset:21504
	ds_read_b128 v[202:205], v157 offset:22528
	ds_read_b128 v[206:209], v157 offset:23552
	global_load_lds_dwordx4 v[152:153], off
	s_add_i32 m0, s45, 0x2000
	s_add_u32 s46, s20, 0x40000
	v_lshl_add_u64 v[210:211], s[20:21], 0, v[130:131]
	s_addc_u32 s47, s21, 0
	s_add_i32 s45, s48, s24
	global_load_lds_dwordx4 v[210:211], off
	v_lshl_add_u64 v[212:213], s[46:47], 0, v[0:1]
	s_mov_b32 m0, s45
	v_lshl_add_u64 v[214:215], s[22:23], 0, v[132:133]
	global_load_lds_dwordx4 v[212:213], off
	v_lshl_add_u64 v[212:213], s[46:47], 0, v[130:131]
	s_add_i32 m0, s45, 0x2000
	s_nop 0
	global_load_lds_dwordx4 v[212:213], off
	v_lshl_add_u64 v[212:213], s[22:23], 0, v[134:135]
	s_mov_b32 m0, s17
	s_nop 0
	global_load_lds_dwordx4 v[212:213], off
	s_mov_b32 m0, s26
	s_nop 0
	global_load_lds_dwordx4 v[214:215], off
	s_waitcnt vmcnt(8)
	s_waitcnt lgkmcnt(0)
	s_setprio 1
	s_barrier
; #define PG8_STAGE(bufoff, gbase, voff) do { _Pragma("unroll") for (int _i = 0; _i < 2; ++_i) \
;         __builtin_amdgcn_global_load_lds((const unsigned*)((const char*)(gbase) + (voff)[_i]), (PG8_LAS unsigned*)(lds + (bufoff) + ldsw + _i * 8192), 16, 0, 0); } while (0)
; #define PG8_LDA(dst, b, h) do { _Pragma("unroll") for (int m = 0; m < 4; ++m) _Pragma("unroll") for (int k = 0; k < 2; ++k) dst[m][k] = *(const PG8_LAS bf16x8*)(lds + PG8_SA(b, h) + aoff + m * 2048 + k * 1024); } while (0)
; #define PG8_LDB(dst, b, h) do { _Pragma("unroll") for (int n = 0; n < 2; ++n) _Pragma("unroll") for (int k = 0; k < 2; ++k) dst[n][k] = *(const PG8_LAS bf16x8*)(lds + PG8_SB(b, h) + boff + n * 2048 + k * 1024); } while (0)
; #define PG8_MMA(ai, bj, At, Bt) do { __builtin_amdgcn_s_setprio(1); _Pragma("unroll") for (int m = 0; m < 4; ++m) _Pragma("unroll") for (int n = 0; n < 2; ++n) _Pragma("unroll") for (int k = 0; k < 2; ++k) \
;         acc[ai][bj][m][n] = __builtin_amdgcn_mfma_f32_16x16x32_bf16(Bt[n][k], At[m][k], acc[ai][bj][m][n], 0, 0, 0); __builtin_amdgcn_s_setprio(0); } while (0)
; #define PG8_WAIT_V(n) asm volatile("s_waitcnt vmcnt(" #n ")" ::: "memory")
; #define PG8_WAIT_L(n) asm volatile("s_waitcnt lgkmcnt(" #n ")" ::: "memory")
; #define PG8_BAR __builtin_amdgcn_s_barrier()
; #define PG8_SCHED __builtin_amdgcn_sched_barrier(0)
; template <class Epi, class Sched, bool ALIGN_EPI = false, bool SP2 = false>
; __device__ __forceinline__ void gemm_phase(PG8_LAS unsigned char* lds, const Gemm g, const Sched& S, const Epi& E, const int wv) {
;     ...
;             PG8_WAIT_V(8); PG8_WAIT_L(0); PG8_BAR; PG8_MMA(1, 0, At, B0); PG8_MMA(1, 1, At, B1); PG8_BAR; PG8_SCHED;
;             PG8_LDB(B0, 1, 0); PG8_LDB(B1, 1, 1); PG8_SCHED; PG8_LDA(At, 1, 0); PG8_STAGE(PG8_SA(0, 1), a2 + hstep, voffA);
;             PG8_WAIT_V(8); PG8_WAIT_L(0); PG8_BAR; PG8_MMA(0, 0, At, B0); PG8_MMA(0, 1, At, B1); PG8_BAR; PG8_SCHED;
	s_waitcnt lgkmcnt(0)
	v_mfma_f32_16x16x32_bf16 v[62:65], v[140:143], v[178:181], v[62:65]
	v_mfma_f32_16x16x32_bf16 v[58:61], v[148:151], v[178:181], v[58:61]
	v_mfma_f32_16x16x32_bf16 v[46:49], v[140:143], v[186:189], v[46:49]
	v_mfma_f32_16x16x32_bf16 v[42:45], v[148:151], v[186:189], v[42:45]
	v_mfma_f32_16x16x32_bf16 v[30:33], v[140:143], v[194:197], v[30:33]
	v_mfma_f32_16x16x32_bf16 v[26:29], v[148:151], v[194:197], v[26:29]
	v_mfma_f32_16x16x32_bf16 v[14:17], v[140:143], v[202:205], v[14:17]
	v_mfma_f32_16x16x32_bf16 v[10:13], v[148:151], v[202:205], v[10:13]
	v_mfma_f32_16x16x32_bf16 v[62:65], v[144:147], v[182:185], v[62:65]
	v_mfma_f32_16x16x32_bf16 v[58:61], v[158:161], v[182:185], v[58:61]
	v_mfma_f32_16x16x32_bf16 v[46:49], v[144:147], v[190:193], v[46:49]
	v_mfma_f32_16x16x32_bf16 v[42:45], v[158:161], v[190:193], v[42:45]
	v_mfma_f32_16x16x32_bf16 v[30:33], v[144:147], v[198:201], v[30:33]
	v_mfma_f32_16x16x32_bf16 v[26:29], v[158:161], v[198:201], v[26:29]
	v_mfma_f32_16x16x32_bf16 v[14:17], v[144:147], v[206:209], v[14:17]
	v_mfma_f32_16x16x32_bf16 v[10:13], v[158:161], v[206:209], v[10:13]
	s_setprio 0
	s_setprio 1
	v_mfma_f32_16x16x32_bf16 v[54:57], v[162:165], v[178:181], v[54:57]
	v_mfma_f32_16x16x32_bf16 v[50:53], v[170:173], v[178:181], v[50:53]
	v_mfma_f32_16x16x32_bf16 v[38:41], v[162:165], v[186:189], v[38:41]
	v_mfma_f32_16x16x32_bf16 v[34:37], v[170:173], v[186:189], v[34:37]
	v_mfma_f32_16x16x32_bf16 v[22:25], v[162:165], v[194:197], v[22:25]
	v_mfma_f32_16x16x32_bf16 v[18:21], v[170:173], v[194:197], v[18:21]
	v_mfma_f32_16x16x32_bf16 v[6:9], v[162:165], v[202:205], v[6:9]
	v_mfma_f32_16x16x32_bf16 v[2:5], v[170:173], v[202:205], v[2:5]
	v_mfma_f32_16x16x32_bf16 v[54:57], v[166:169], v[182:185], v[54:57]
	v_mfma_f32_16x16x32_bf16 v[50:53], v[174:177], v[182:185], v[50:53]
	v_mfma_f32_16x16x32_bf16 v[38:41], v[166:169], v[190:193], v[38:41]
	v_mfma_f32_16x16x32_bf16 v[34:37], v[174:177], v[190:193], v[34:37]
	v_mfma_f32_16x16x32_bf16 v[22:25], v[166:169], v[198:201], v[22:25]
	v_mfma_f32_16x16x32_bf16 v[18:21], v[174:177], v[198:201], v[18:21]
	v_mfma_f32_16x16x32_bf16 v[6:9], v[166:169], v[206:209], v[6:9]
	v_mfma_f32_16x16x32_bf16 v[2:5], v[174:177], v[206:209], v[2:5]
	s_barrier
	s_setprio 0
	s_add_i32 s45, 0, 0x18000
	s_add_i32 s46, 0, 0x1c000
	v_add_u32_e32 v158, s45, v155
	v_add_u32_e32 v174, s46, v155
	ds_read_b128 v[140:143], v158
	ds_read_b128 v[144:147], v158 offset:1024
	ds_read_b128 v[148:151], v158 offset:2048
	ds_read_b128 v[158:161], v158 offset:3072
	ds_read_b128 v[162:165], v174
	ds_read_b128 v[166:169], v174 offset:1024
	ds_read_b128 v[170:173], v174 offset:2048
	ds_read_b128 v[174:177], v174 offset:3072
	s_add_u32 s22, s22, 0x40000
	s_addc_u32 s23, s23, 0
	s_mov_b32 m0, s27
	v_lshl_add_u64 v[216:217], s[22:23], 0, v[134:135]
	ds_read_b128 v[178:181], v157 offset:32768
	ds_read_b128 v[182:185], v157 offset:33792
	ds_read_b128 v[186:189], v157 offset:34816
	ds_read_b128 v[190:193], v157 offset:35840
	ds_read_b128 v[194:197], v157 offset:36864
	ds_read_b128 v[198:201], v157 offset:37888
	ds_read_b128 v[202:205], v157 offset:38912
	ds_read_b128 v[206:209], v157 offset:39936
	global_load_lds_dwordx4 v[216:217], off
	v_lshl_add_u64 v[216:217], s[22:23], 0, v[132:133]
	s_mov_b32 m0, s28
	s_nop 0
	global_load_lds_dwordx4 v[216:217], off
	s_waitcnt vmcnt(8)
	s_waitcnt lgkmcnt(0)
	s_setprio 1
	s_barrier
	s_waitcnt lgkmcnt(0)
	v_mfma_f32_16x16x32_bf16 v[126:129], v[140:143], v[178:181], v[126:129]
	v_mfma_f32_16x16x32_bf16 v[122:125], v[148:151], v[178:181], v[122:125]
	v_mfma_f32_16x16x32_bf16 v[118:121], v[140:143], v[186:189], v[118:121]
	v_mfma_f32_16x16x32_bf16 v[114:117], v[148:151], v[186:189], v[114:117]
	v_mfma_f32_16x16x32_bf16 v[98:101], v[140:143], v[194:197], v[98:101]
	v_mfma_f32_16x16x32_bf16 v[90:93], v[148:151], v[194:197], v[90:93]
	v_mfma_f32_16x16x32_bf16 v[78:81], v[140:143], v[202:205], v[78:81]
	v_mfma_f32_16x16x32_bf16 v[74:77], v[148:151], v[202:205], v[74:77]
	v_mfma_f32_16x16x32_bf16 v[126:129], v[144:147], v[182:185], v[126:129]
	v_mfma_f32_16x16x32_bf16 v[122:125], v[158:161], v[182:185], v[122:125]
	v_mfma_f32_16x16x32_bf16 v[118:121], v[144:147], v[190:193], v[118:121]
	v_mfma_f32_16x16x32_bf16 v[114:117], v[158:161], v[190:193], v[114:117]
	v_mfma_f32_16x16x32_bf16 v[98:101], v[144:147], v[198:201], v[98:101]
	v_mfma_f32_16x16x32_bf16 v[90:93], v[158:161], v[198:201], v[90:93]
	v_mfma_f32_16x16x32_bf16 v[78:81], v[144:147], v[206:209], v[78:81]
	v_mfma_f32_16x16x32_bf16 v[74:77], v[158:161], v[206:209], v[74:77]
	s_setprio 0
	s_setprio 1
	v_mfma_f32_16x16x32_bf16 v[110:113], v[162:165], v[178:181], v[110:113]
	v_mfma_f32_16x16x32_bf16 v[106:109], v[170:173], v[178:181], v[106:109]
	v_mfma_f32_16x16x32_bf16 v[102:105], v[162:165], v[186:189], v[102:105]
	v_mfma_f32_16x16x32_bf16 v[94:97], v[170:173], v[186:189], v[94:97]
	v_mfma_f32_16x16x32_bf16 v[86:89], v[162:165], v[194:197], v[86:89]
	v_mfma_f32_16x16x32_bf16 v[82:85], v[170:173], v[194:197], v[82:85]
	v_mfma_f32_16x16x32_bf16 v[70:73], v[162:165], v[202:205], v[70:73]
	v_mfma_f32_16x16x32_bf16 v[66:69], v[170:173], v[202:205], v[66:69]
	v_mfma_f32_16x16x32_bf16 v[110:113], v[166:169], v[182:185], v[110:113]
	v_mfma_f32_16x16x32_bf16 v[106:109], v[174:177], v[182:185], v[106:109]
	v_mfma_f32_16x16x32_bf16 v[102:105], v[166:169], v[190:193], v[102:105]
	v_mfma_f32_16x16x32_bf16 v[94:97], v[174:177], v[190:193], v[94:97]
	v_mfma_f32_16x16x32_bf16 v[86:89], v[166:169], v[198:201], v[86:89]
	v_mfma_f32_16x16x32_bf16 v[82:85], v[174:177], v[198:201], v[82:85]
	v_mfma_f32_16x16x32_bf16 v[70:73], v[166:169], v[206:209], v[70:73]
	v_mfma_f32_16x16x32_bf16 v[66:69], v[174:177], v[206:209], v[66:69]
	s_barrier
; #define PG8_STAGE(bufoff, gbase, voff) do { _Pragma("unroll") for (int _i = 0; _i < 2; ++_i) \
;         __builtin_amdgcn_global_load_lds((const unsigned*)((const char*)(gbase) + (voff)[_i]), (PG8_LAS unsigned*)(lds + (bufoff) + ldsw + _i * 8192), 16, 0, 0); } while (0)
; #define PG8_LDA(dst, b, h) do { _Pragma("unroll") for (int m = 0; m < 4; ++m) _Pragma("unroll") for (int k = 0; k < 2; ++k) dst[m][k] = *(const PG8_LAS bf16x8*)(lds + PG8_SA(b, h) + aoff + m * 2048 + k * 1024); } while (0)
; #define PG8_MMA(ai, bj, At, Bt) do { __builtin_amdgcn_s_setprio(1); _Pragma("unroll") for (int m = 0; m < 4; ++m) _Pragma("unroll") for (int n = 0; n < 2; ++n) _Pragma("unroll") for (int k = 0; k < 2; ++k) \
;         acc[ai][bj][m][n] = __builtin_amdgcn_mfma_f32_16x16x32_bf16(Bt[n][k], At[m][k], acc[ai][bj][m][n], 0, 0, 0); __builtin_amdgcn_s_setprio(0); } while (0)
; #define PG8_WAIT_V(n) asm volatile("s_waitcnt vmcnt(" #n ")" ::: "memory")
; #define PG8_WAIT_L(n) asm volatile("s_waitcnt lgkmcnt(" #n ")" ::: "memory")
; #define PG8_BAR __builtin_amdgcn_s_barrier()
; #define PG8_SCHED __builtin_amdgcn_sched_barrier(0)
; template <class Epi, class Sched, bool ALIGN_EPI = false, bool SP2 = false>
; __device__ __forceinline__ void gemm_phase(PG8_LAS unsigned char* lds, const Gemm g, const Sched& S, const Epi& E, const int wv) {
;     ...
;             PG8_LDA(At, 1, 1); PG8_STAGE(PG8_SB(1, 0), b3, voffB); PG8_STAGE(PG8_SB(1, 1), b3 + hstep, voffB); PG8_STAGE(PG8_SA(1, 0), a3, voffA);
;             PG8_WAIT_V(8); PG8_WAIT_L(0); PG8_BAR; PG8_MMA(1, 0, At, B0); PG8_MMA(1, 1, At, B1); PG8_BAR; PG8_SCHED;
;     ...
;         if constexpr (ALIGN_EPI) { if (wr == 0) PG8_BAR; }
	s_setprio 0
	s_add_i32 s22, s45, s24
	v_lshl_add_u64 v[152:153], v[152:153], 0, s[2:3]
	s_mov_b32 m0, s22
	ds_read_b128 v[178:181], v157 offset:49152
	ds_read_b128 v[182:185], v157 offset:50176
	ds_read_b128 v[186:189], v157 offset:51200
	ds_read_b128 v[190:193], v157 offset:52224
	ds_read_b128 v[194:197], v157 offset:53248
	ds_read_b128 v[198:201], v157 offset:54272
	ds_read_b128 v[202:205], v157 offset:55296
	ds_read_b128 v[206:209], v157 offset:56320
	global_load_lds_dwordx4 v[152:153], off
	s_add_i32 m0, s22, 0x2000
	s_add_u32 s20, s20, 0x40080
	v_lshl_add_u64 v[152:153], v[210:211], 0, s[2:3]
	s_addc_u32 s21, s21, 0
	s_add_i32 s22, s46, s24
	global_load_lds_dwordx4 v[152:153], off
	v_lshl_add_u64 v[152:153], s[20:21], 0, v[0:1]
	s_mov_b32 m0, s22
	s_nop 0
	global_load_lds_dwordx4 v[152:153], off
	v_lshl_add_u64 v[152:153], s[20:21], 0, v[130:131]
	s_add_i32 m0, s22, 0x2000
	s_nop 0
	global_load_lds_dwordx4 v[152:153], off
	v_lshl_add_u64 v[152:153], v[212:213], 0, s[2:3]
	s_mov_b32 m0, s33
	s_nop 0
	global_load_lds_dwordx4 v[152:153], off
	v_lshl_add_u64 v[152:153], v[214:215], 0, s[2:3]
	s_mov_b32 m0, s35
	s_nop 0
	global_load_lds_dwordx4 v[152:153], off
	s_waitcnt vmcnt(8)
	s_waitcnt lgkmcnt(0)
	s_setprio 1
	s_barrier
	s_waitcnt lgkmcnt(0)
	v_mfma_f32_16x16x32_bf16 v[62:65], v[140:143], v[178:181], v[62:65]
	v_mfma_f32_16x16x32_bf16 v[58:61], v[148:151], v[178:181], v[58:61]
	v_mfma_f32_16x16x32_bf16 v[46:49], v[140:143], v[186:189], v[46:49]
	v_mfma_f32_16x16x32_bf16 v[42:45], v[148:151], v[186:189], v[42:45]
	v_mfma_f32_16x16x32_bf16 v[30:33], v[140:143], v[194:197], v[30:33]
	v_mfma_f32_16x16x32_bf16 v[26:29], v[148:151], v[194:197], v[26:29]
	v_mfma_f32_16x16x32_bf16 v[14:17], v[140:143], v[202:205], v[14:17]
	v_mfma_f32_16x16x32_bf16 v[10:13], v[148:151], v[202:205], v[10:13]
	v_mfma_f32_16x16x32_bf16 v[62:65], v[144:147], v[182:185], v[62:65]
	v_mfma_f32_16x16x32_bf16 v[58:61], v[158:161], v[182:185], v[58:61]
	v_mfma_f32_16x16x32_bf16 v[46:49], v[144:147], v[190:193], v[46:49]
	v_mfma_f32_16x16x32_bf16 v[42:45], v[158:161], v[190:193], v[42:45]
	v_mfma_f32_16x16x32_bf16 v[30:33], v[144:147], v[198:201], v[30:33]
	v_mfma_f32_16x16x32_bf16 v[26:29], v[158:161], v[198:201], v[26:29]
	v_mfma_f32_16x16x32_bf16 v[14:17], v[144:147], v[206:209], v[14:17]
	v_mfma_f32_16x16x32_bf16 v[10:13], v[158:161], v[206:209], v[10:13]
	s_setprio 0
	s_setprio 1
	v_mfma_f32_16x16x32_bf16 v[54:57], v[162:165], v[178:181], v[54:57]
	v_mfma_f32_16x16x32_bf16 v[50:53], v[170:173], v[178:181], v[50:53]
	v_mfma_f32_16x16x32_bf16 v[38:41], v[162:165], v[186:189], v[38:41]
	v_mfma_f32_16x16x32_bf16 v[34:37], v[170:173], v[186:189], v[34:37]
	v_mfma_f32_16x16x32_bf16 v[22:25], v[162:165], v[194:197], v[22:25]
	v_mfma_f32_16x16x32_bf16 v[18:21], v[170:173], v[194:197], v[18:21]
	v_mfma_f32_16x16x32_bf16 v[6:9], v[162:165], v[202:205], v[6:9]
	v_mfma_f32_16x16x32_bf16 v[2:5], v[170:173], v[202:205], v[2:5]
	v_mfma_f32_16x16x32_bf16 v[54:57], v[166:169], v[182:185], v[54:57]
	v_mfma_f32_16x16x32_bf16 v[50:53], v[174:177], v[182:185], v[50:53]
	v_mfma_f32_16x16x32_bf16 v[38:41], v[166:169], v[190:193], v[38:41]
	v_mfma_f32_16x16x32_bf16 v[34:37], v[174:177], v[190:193], v[34:37]
	v_mfma_f32_16x16x32_bf16 v[22:25], v[166:169], v[198:201], v[22:25]
	v_mfma_f32_16x16x32_bf16 v[18:21], v[174:177], v[198:201], v[18:21]
	v_mfma_f32_16x16x32_bf16 v[6:9], v[166:169], v[206:209], v[6:9]
	v_mfma_f32_16x16x32_bf16 v[2:5], v[174:177], v[206:209], v[2:5]
	s_barrier
	s_setprio 0
	s_add_i32 s44, s44, 2
	s_add_u32 s18, s18, 0x100
	s_addc_u32 s19, s19, 0
	s_add_u32 s42, s42, 0x100
	s_addc_u32 s43, s43, 0
	s_cmp_gt_u32 s44, 13
	s_cbranch_scc0 .LBB0_156
	s_and_b64 vcc, exec, s[6:7]
	s_cbranch_vccz .LBB0_159
	s_barrier

; #define PG8_STAGE(bufoff, gbase, voff) do { _Pragma("unroll") for (int _i = 0; _i < 2; ++_i) \
;         __builtin_amdgcn_global_load_lds((const unsigned*)((const char*)(gbase) + (voff)[_i]), (PG8_LAS unsigned*)(lds + (bufoff) + ldsw + _i * 8192), 16, 0, 0); } while (0)
; #define PG8_LDA(dst, b, h) do { _Pragma("unroll") for (int m = 0; m < 4; ++m) _Pragma("unroll") for (int k = 0; k < 2; ++k) dst[m][k] = *(const PG8_LAS bf16x8*)(lds + PG8_SA(b, h) + aoff + m * 2048 + k * 1024); } while (0)
; #define PG8_LDB(dst, b, h) do { _Pragma("unroll") for (int n = 0; n < 2; ++n) _Pragma("unroll") for (int k = 0; k < 2; ++k) dst[n][k] = *(const PG8_LAS bf16x8*)(lds + PG8_SB(b, h) + boff + n * 2048 + k * 1024); } while (0)
; #define PG8_MMA(ai, bj, At, Bt) do { __builtin_amdgcn_s_setprio(1); _Pragma("unroll") for (int m = 0; m < 4; ++m) _Pragma("unroll") for (int n = 0; n < 2; ++n) _Pragma("unroll") for (int k = 0; k < 2; ++k) \
;         acc[ai][bj][m][n] = __builtin_amdgcn_mfma_f32_16x16x32_bf16(Bt[n][k], At[m][k], acc[ai][bj][m][n], 0, 0, 0); __builtin_amdgcn_s_setprio(0); } while (0)
; #define PG8_WAIT_V(n) asm volatile("s_waitcnt vmcnt(" #n ")" ::: "memory")
; #define PG8_WAIT_L(n) asm volatile("s_waitcnt lgkmcnt(" #n ")" ::: "memory")
; #define PG8_BAR __builtin_amdgcn_s_barrier()
; #define PG8_SCHED __builtin_amdgcn_sched_barrier(0)
; template <class Epi, class Sched, bool ALIGN_EPI = false, bool SP2 = false>
; __device__ __forceinline__ void gemm_phase(PG8_LAS unsigned char* lds, const Gemm g, const Sched& S, const Epi& E, const int wv) {
;     ...
;             const bool last = (t == nt - 2);
;             const char* a1 = cA + (size_t)(t + 1) * kstep;
;             const char* a2 = last ? nA : cA + (size_t)(t + 2) * kstep; const char* b2 = last ? nB : cB + (size_t)(t + 2) * kstep;
;             const char* a3 = a2 + kstep; const char* b3 = b2 + kstep;
;             if (last && has_next) S.a_ready(nxt);
;             if constexpr (SP2) {
;             PG8_LDB(B0, 0, 0); PG8_LDB(B1, 0, 1); PG8_SCHED; PG8_LDA(At, 0, 0); PG8_STAGE(PG8_SA(1, 1), a1 + hstep, voffA);
;             PG8_WAIT_V(8); PG8_WAIT_L(0); PG8_BAR; PG8_MMA(0, 0, At, B0); PG8_MMA(0, 1, At, B1); PG8_BAR; PG8_SCHED;
;             PG8_LDA(At, 0, 1); PG8_STAGE(PG8_SB(0, 0), b2, voffB); PG8_STAGE(PG8_SB(0, 1), b2 + hstep, voffB); PG8_STAGE(PG8_SA(0, 0), a2, voffA);
.LBB0_350:
	s_add_u32 s24, s22, 0xfffc0080
	s_addc_u32 s25, s23, -1
	s_add_i32 s48, 0, 0x10000
	s_cmp_eq_u32 s47, 12
	s_cselect_b32 s27, s13, s25
	s_cselect_b32 s26, s19, s24
	s_cselect_b32 s25, s11, s46
	s_cselect_b32 s24, s33, s45
	s_add_i32 s50, 0, 0x14000
	v_add_u32_e32 v126, s48, v183
	v_add_u32_e32 v168, s50, v183
	ds_read_b128 v[114:117], v126
	ds_read_b128 v[118:121], v126 offset:1024
	ds_read_b128 v[122:125], v126 offset:2048
	ds_read_b128 v[126:129], v126 offset:3072
	ds_read_b128 v[130:133], v168
	ds_read_b128 v[134:137], v168 offset:1024
	ds_read_b128 v[164:167], v168 offset:2048
	ds_read_b128 v[168:171], v168 offset:3072
	v_lshl_add_u64 v[180:181], s[22:23], 0, v[160:161]
	s_add_i32 m0, s21, 0xc000
	ds_read_b128 v[172:175], v185
	ds_read_b128 v[176:179], v185 offset:1024
	ds_read_b128 v[186:189], v185 offset:2048
	ds_read_b128 v[190:193], v185 offset:3072
	ds_read_b128 v[194:197], v185 offset:4096
	ds_read_b128 v[198:201], v185 offset:5120
	ds_read_b128 v[202:205], v185 offset:6144
	ds_read_b128 v[206:209], v185 offset:7168
	global_load_lds_dwordx4 v[180:181], off
	v_lshl_add_u64 v[180:181], s[22:23], 0, v[162:163]
	s_add_i32 m0, s21, 0xe000
	s_nop 0
	global_load_lds_dwordx4 v[180:181], off
	s_waitcnt vmcnt(8)
	s_waitcnt lgkmcnt(0)
	s_setprio 1
	s_barrier
	s_waitcnt lgkmcnt(0)
	v_mfma_f32_16x16x32_bf16 v[150:153], v[114:117], v[172:175], v[150:153]
	v_mfma_f32_16x16x32_bf16 v[146:149], v[122:125], v[172:175], v[146:149]
	v_mfma_f32_16x16x32_bf16 v[110:113], v[114:117], v[186:189], v[110:113]
	v_mfma_f32_16x16x32_bf16 v[106:109], v[122:125], v[186:189], v[106:109]
	v_mfma_f32_16x16x32_bf16 v[94:97], v[114:117], v[194:197], v[94:97]
	v_mfma_f32_16x16x32_bf16 v[90:93], v[122:125], v[194:197], v[90:93]
	v_mfma_f32_16x16x32_bf16 v[78:81], v[114:117], v[202:205], v[78:81]
	v_mfma_f32_16x16x32_bf16 v[74:77], v[122:125], v[202:205], v[74:77]
	v_mfma_f32_16x16x32_bf16 v[150:153], v[118:121], v[176:179], v[150:153]
	v_mfma_f32_16x16x32_bf16 v[146:149], v[126:129], v[176:179], v[146:149]
	v_mfma_f32_16x16x32_bf16 v[110:113], v[118:121], v[190:193], v[110:113]
	v_mfma_f32_16x16x32_bf16 v[106:109], v[126:129], v[190:193], v[106:109]
	v_mfma_f32_16x16x32_bf16 v[94:97], v[118:121], v[198:201], v[94:97]
	v_mfma_f32_16x16x32_bf16 v[90:93], v[126:129], v[198:201], v[90:93]
	v_mfma_f32_16x16x32_bf16 v[78:81], v[118:121], v[206:209], v[78:81]
	v_mfma_f32_16x16x32_bf16 v[74:77], v[126:129], v[206:209], v[74:77]
	s_setprio 0
	s_setprio 1
	v_mfma_f32_16x16x32_bf16 v[142:145], v[130:133], v[172:175], v[142:145]
	v_mfma_f32_16x16x32_bf16 v[138:141], v[164:167], v[172:175], v[138:141]
	v_mfma_f32_16x16x32_bf16 v[102:105], v[130:133], v[186:189], v[102:105]
	v_mfma_f32_16x16x32_bf16 v[98:101], v[164:167], v[186:189], v[98:101]
	v_mfma_f32_16x16x32_bf16 v[86:89], v[130:133], v[194:197], v[86:89]
	v_mfma_f32_16x16x32_bf16 v[82:85], v[164:167], v[194:197], v[82:85]
	v_mfma_f32_16x16x32_bf16 v[70:73], v[130:133], v[202:205], v[70:73]
	v_mfma_f32_16x16x32_bf16 v[66:69], v[164:167], v[202:205], v[66:69]
	v_mfma_f32_16x16x32_bf16 v[142:145], v[134:137], v[176:179], v[142:145]
	v_mfma_f32_16x16x32_bf16 v[138:141], v[168:171], v[176:179], v[138:141]
	v_mfma_f32_16x16x32_bf16 v[102:105], v[134:137], v[190:193], v[102:105]
	v_mfma_f32_16x16x32_bf16 v[98:101], v[168:171], v[190:193], v[98:101]
	v_mfma_f32_16x16x32_bf16 v[86:89], v[134:137], v[198:201], v[86:89]
	v_mfma_f32_16x16x32_bf16 v[82:85], v[168:171], v[198:201], v[82:85]
	v_mfma_f32_16x16x32_bf16 v[70:73], v[134:137], v[206:209], v[70:73]
	v_mfma_f32_16x16x32_bf16 v[66:69], v[168:171], v[206:209], v[66:69]
	s_barrier
	s_setprio 0
	s_add_i32 s48, s48, s36
	v_lshl_add_u64 v[180:181], s[24:25], 0, v[0:1]
	s_mov_b32 m0, s48
	ds_read_b128 v[172:175], v185 offset:16384
	ds_read_b128 v[176:179], v185 offset:17408
	ds_read_b128 v[186:189], v185 offset:18432
	ds_read_b128 v[190:193], v185 offset:19456
	ds_read_b128 v[194:197], v185 offset:20480
	ds_read_b128 v[198:201], v185 offset:21504
	ds_read_b128 v[202:205], v185 offset:22528
	ds_read_b128 v[206:209], v185 offset:23552
	global_load_lds_dwordx4 v[180:181], off
	s_add_i32 m0, s48, 0x2000
	s_add_u32 s48, s24, 0x40000
	v_lshl_add_u64 v[210:211], s[24:25], 0, v[158:159]
	s_addc_u32 s49, s25, 0
	s_add_i32 s50, s50, s36
	global_load_lds_dwordx4 v[210:211], off
	v_lshl_add_u64 v[212:213], s[48:49], 0, v[0:1]
	s_mov_b32 m0, s50
	v_lshl_add_u64 v[214:215], s[26:27], 0, v[156:157]
	global_load_lds_dwordx4 v[212:213], off
	v_lshl_add_u64 v[212:213], s[48:49], 0, v[158:159]
	s_add_i32 m0, s50, 0x2000
	s_nop 0
	global_load_lds_dwordx4 v[212:213], off
	v_lshl_add_u64 v[212:213], s[26:27], 0, v[154:155]
	s_mov_b32 m0, s21
	s_nop 0
	global_load_lds_dwordx4 v[212:213], off
	s_mov_b32 m0, s37
	s_nop 0
	global_load_lds_dwordx4 v[214:215], off
	s_waitcnt vmcnt(8)
	s_waitcnt lgkmcnt(0)
	s_setprio 1
	s_barrier
; #define PG8_STAGE(bufoff, gbase, voff) do { _Pragma("unroll") for (int _i = 0; _i < 2; ++_i) \
;         __builtin_amdgcn_global_load_lds((const unsigned*)((const char*)(gbase) + (voff)[_i]), (PG8_LAS unsigned*)(lds + (bufoff) + ldsw + _i * 8192), 16, 0, 0); } while (0)
; #define PG8_LDA(dst, b, h) do { _Pragma("unroll") for (int m = 0; m < 4; ++m) _Pragma("unroll") for (int k = 0; k < 2; ++k) dst[m][k] = *(const PG8_LAS bf16x8*)(lds + PG8_SA(b, h) + aoff + m * 2048 + k * 1024); } while (0)
; #define PG8_LDB(dst, b, h) do { _Pragma("unroll") for (int n = 0; n < 2; ++n) _Pragma("unroll") for (int k = 0; k < 2; ++k) dst[n][k] = *(const PG8_LAS bf16x8*)(lds + PG8_SB(b, h) + boff + n * 2048 + k * 1024); } while (0)
; #define PG8_MMA(ai, bj, At, Bt) do { __builtin_amdgcn_s_setprio(1); _Pragma("unroll") for (int m = 0; m < 4; ++m) _Pragma("unroll") for (int n = 0; n < 2; ++n) _Pragma("unroll") for (int k = 0; k < 2; ++k) \
;         acc[ai][bj][m][n] = __builtin_amdgcn_mfma_f32_16x16x32_bf16(Bt[n][k], At[m][k], acc[ai][bj][m][n], 0, 0, 0); __builtin_amdgcn_s_setprio(0); } while (0)
; #define PG8_WAIT_V(n) asm volatile("s_waitcnt vmcnt(" #n ")" ::: "memory")
; #define PG8_WAIT_L(n) asm volatile("s_waitcnt lgkmcnt(" #n ")" ::: "memory")
; #define PG8_BAR __builtin_amdgcn_s_barrier()
; #define PG8_SCHED __builtin_amdgcn_sched_barrier(0)
; template <class Epi, class Sched, bool ALIGN_EPI = false, bool SP2 = false>
; __device__ __forceinline__ void gemm_phase(PG8_LAS unsigned char* lds, const Gemm g, const Sched& S, const Epi& E, const int wv) {
;     ...
;             PG8_WAIT_V(8); PG8_WAIT_L(0); PG8_BAR; PG8_MMA(1, 0, At, B0); PG8_MMA(1, 1, At, B1); PG8_BAR; PG8_SCHED;
;             PG8_LDB(B0, 1, 0); PG8_LDB(B1, 1, 1); PG8_SCHED; PG8_LDA(At, 1, 0); PG8_STAGE(PG8_SA(0, 1), a2 + hstep, voffA);
;             PG8_WAIT_V(8); PG8_WAIT_L(0); PG8_BAR; PG8_MMA(0, 0, At, B0); PG8_MMA(0, 1, At, B1); PG8_BAR; PG8_SCHED;
	s_waitcnt lgkmcnt(0)
	v_mfma_f32_16x16x32_bf16 v[62:65], v[114:117], v[172:175], v[62:65]
	v_mfma_f32_16x16x32_bf16 v[58:61], v[122:125], v[172:175], v[58:61]
	v_mfma_f32_16x16x32_bf16 v[46:49], v[114:117], v[186:189], v[46:49]
	v_mfma_f32_16x16x32_bf16 v[42:45], v[122:125], v[186:189], v[42:45]
	v_mfma_f32_16x16x32_bf16 v[30:33], v[114:117], v[194:197], v[30:33]
	v_mfma_f32_16x16x32_bf16 v[26:29], v[122:125], v[194:197], v[26:29]
	v_mfma_f32_16x16x32_bf16 v[14:17], v[114:117], v[202:205], v[14:17]
	v_mfma_f32_16x16x32_bf16 v[10:13], v[122:125], v[202:205], v[10:13]
	v_mfma_f32_16x16x32_bf16 v[62:65], v[118:121], v[176:179], v[62:65]
	v_mfma_f32_16x16x32_bf16 v[58:61], v[126:129], v[176:179], v[58:61]
	v_mfma_f32_16x16x32_bf16 v[46:49], v[118:121], v[190:193], v[46:49]
	v_mfma_f32_16x16x32_bf16 v[42:45], v[126:129], v[190:193], v[42:45]
	v_mfma_f32_16x16x32_bf16 v[30:33], v[118:121], v[198:201], v[30:33]
	v_mfma_f32_16x16x32_bf16 v[26:29], v[126:129], v[198:201], v[26:29]
	v_mfma_f32_16x16x32_bf16 v[14:17], v[118:121], v[206:209], v[14:17]
	v_mfma_f32_16x16x32_bf16 v[10:13], v[126:129], v[206:209], v[10:13]
	s_setprio 0
	s_setprio 1
	v_mfma_f32_16x16x32_bf16 v[54:57], v[130:133], v[172:175], v[54:57]
	v_mfma_f32_16x16x32_bf16 v[50:53], v[164:167], v[172:175], v[50:53]
	v_mfma_f32_16x16x32_bf16 v[38:41], v[130:133], v[186:189], v[38:41]
	v_mfma_f32_16x16x32_bf16 v[34:37], v[164:167], v[186:189], v[34:37]
	v_mfma_f32_16x16x32_bf16 v[22:25], v[130:133], v[194:197], v[22:25]
	v_mfma_f32_16x16x32_bf16 v[18:21], v[164:167], v[194:197], v[18:21]
	v_mfma_f32_16x16x32_bf16 v[6:9], v[130:133], v[202:205], v[6:9]
	v_mfma_f32_16x16x32_bf16 v[2:5], v[164:167], v[202:205], v[2:5]
	v_mfma_f32_16x16x32_bf16 v[54:57], v[134:137], v[176:179], v[54:57]
	v_mfma_f32_16x16x32_bf16 v[50:53], v[168:171], v[176:179], v[50:53]
	v_mfma_f32_16x16x32_bf16 v[38:41], v[134:137], v[190:193], v[38:41]
	v_mfma_f32_16x16x32_bf16 v[34:37], v[168:171], v[190:193], v[34:37]
	v_mfma_f32_16x16x32_bf16 v[22:25], v[134:137], v[198:201], v[22:25]
	v_mfma_f32_16x16x32_bf16 v[18:21], v[168:171], v[198:201], v[18:21]
	v_mfma_f32_16x16x32_bf16 v[6:9], v[134:137], v[206:209], v[6:9]
	v_mfma_f32_16x16x32_bf16 v[2:5], v[168:171], v[206:209], v[2:5]
	s_barrier
	s_setprio 0
	s_add_i32 s48, 0, 0x18000
	s_add_i32 s49, 0, 0x1c000
	v_add_u32_e32 v126, s48, v183
	v_add_u32_e32 v168, s49, v183
	ds_read_b128 v[114:117], v126
	ds_read_b128 v[118:121], v126 offset:1024
	ds_read_b128 v[122:125], v126 offset:2048
	ds_read_b128 v[126:129], v126 offset:3072
	ds_read_b128 v[130:133], v168
	ds_read_b128 v[134:137], v168 offset:1024
	ds_read_b128 v[164:167], v168 offset:2048
	ds_read_b128 v[168:171], v168 offset:3072
	s_add_u32 s26, s26, 0x40000
	s_addc_u32 s27, s27, 0
	s_mov_b32 m0, s38
	v_lshl_add_u64 v[216:217], s[26:27], 0, v[154:155]
	ds_read_b128 v[172:175], v185 offset:32768
	ds_read_b128 v[176:179], v185 offset:33792
	ds_read_b128 v[186:189], v185 offset:34816
	ds_read_b128 v[190:193], v185 offset:35840
	ds_read_b128 v[194:197], v185 offset:36864
	ds_read_b128 v[198:201], v185 offset:37888
	ds_read_b128 v[202:205], v185 offset:38912
	ds_read_b128 v[206:209], v185 offset:39936
	global_load_lds_dwordx4 v[216:217], off
	v_lshl_add_u64 v[216:217], s[26:27], 0, v[156:157]
	s_mov_b32 m0, s39
	s_nop 0
	global_load_lds_dwordx4 v[216:217], off
	s_waitcnt vmcnt(8)
	s_waitcnt lgkmcnt(0)
	s_setprio 1
	s_barrier
	s_waitcnt lgkmcnt(0)
	v_mfma_f32_16x16x32_bf16 v[150:153], v[114:117], v[172:175], v[150:153]
	v_mfma_f32_16x16x32_bf16 v[146:149], v[122:125], v[172:175], v[146:149]
	v_mfma_f32_16x16x32_bf16 v[110:113], v[114:117], v[186:189], v[110:113]
	v_mfma_f32_16x16x32_bf16 v[106:109], v[122:125], v[186:189], v[106:109]
	v_mfma_f32_16x16x32_bf16 v[94:97], v[114:117], v[194:197], v[94:97]
	v_mfma_f32_16x16x32_bf16 v[90:93], v[122:125], v[194:197], v[90:93]
	v_mfma_f32_16x16x32_bf16 v[78:81], v[114:117], v[202:205], v[78:81]
	v_mfma_f32_16x16x32_bf16 v[74:77], v[122:125], v[202:205], v[74:77]
	v_mfma_f32_16x16x32_bf16 v[150:153], v[118:121], v[176:179], v[150:153]
	v_mfma_f32_16x16x32_bf16 v[146:149], v[126:129], v[176:179], v[146:149]
	v_mfma_f32_16x16x32_bf16 v[110:113], v[118:121], v[190:193], v[110:113]
	v_mfma_f32_16x16x32_bf16 v[106:109], v[126:129], v[190:193], v[106:109]
	v_mfma_f32_16x16x32_bf16 v[94:97], v[118:121], v[198:201], v[94:97]
	v_mfma_f32_16x16x32_bf16 v[90:93], v[126:129], v[198:201], v[90:93]
	v_mfma_f32_16x16x32_bf16 v[78:81], v[118:121], v[206:209], v[78:81]
	v_mfma_f32_16x16x32_bf16 v[74:77], v[126:129], v[206:209], v[74:77]
	s_setprio 0
	s_setprio 1
	v_mfma_f32_16x16x32_bf16 v[142:145], v[130:133], v[172:175], v[142:145]
	v_mfma_f32_16x16x32_bf16 v[138:141], v[164:167], v[172:175], v[138:141]
	v_mfma_f32_16x16x32_bf16 v[102:105], v[130:133], v[186:189], v[102:105]
	v_mfma_f32_16x16x32_bf16 v[98:101], v[164:167], v[186:189], v[98:101]
	v_mfma_f32_16x16x32_bf16 v[86:89], v[130:133], v[194:197], v[86:89]
	v_mfma_f32_16x16x32_bf16 v[82:85], v[164:167], v[194:197], v[82:85]
	v_mfma_f32_16x16x32_bf16 v[70:73], v[130:133], v[202:205], v[70:73]
	v_mfma_f32_16x16x32_bf16 v[66:69], v[164:167], v[202:205], v[66:69]
	v_mfma_f32_16x16x32_bf16 v[142:145], v[134:137], v[176:179], v[142:145]
	v_mfma_f32_16x16x32_bf16 v[138:141], v[168:171], v[176:179], v[138:141]
	v_mfma_f32_16x16x32_bf16 v[102:105], v[134:137], v[190:193], v[102:105]
	v_mfma_f32_16x16x32_bf16 v[98:101], v[168:171], v[190:193], v[98:101]
	v_mfma_f32_16x16x32_bf16 v[86:89], v[134:137], v[198:201], v[86:89]
	v_mfma_f32_16x16x32_bf16 v[82:85], v[168:171], v[198:201], v[82:85]
	v_mfma_f32_16x16x32_bf16 v[70:73], v[134:137], v[206:209], v[70:73]
	v_mfma_f32_16x16x32_bf16 v[66:69], v[168:171], v[206:209], v[66:69]
	s_barrier
; #define PG8_STAGE(bufoff, gbase, voff) do { _Pragma("unroll") for (int _i = 0; _i < 2; ++_i) \
;         __builtin_amdgcn_global_load_lds((const unsigned*)((const char*)(gbase) + (voff)[_i]), (PG8_LAS unsigned*)(lds + (bufoff) + ldsw + _i * 8192), 16, 0, 0); } while (0)
; #define PG8_LDA(dst, b, h) do { _Pragma("unroll") for (int m = 0; m < 4; ++m) _Pragma("unroll") for (int k = 0; k < 2; ++k) dst[m][k] = *(const PG8_LAS bf16x8*)(lds + PG8_SA(b, h) + aoff + m * 2048 + k * 1024); } while (0)
; #define PG8_MMA(ai, bj, At, Bt) do { __builtin_amdgcn_s_setprio(1); _Pragma("unroll") for (int m = 0; m < 4; ++m) _Pragma("unroll") for (int n = 0; n < 2; ++n) _Pragma("unroll") for (int k = 0; k < 2; ++k) \
;         acc[ai][bj][m][n] = __builtin_amdgcn_mfma_f32_16x16x32_bf16(Bt[n][k], At[m][k], acc[ai][bj][m][n], 0, 0, 0); __builtin_amdgcn_s_setprio(0); } while (0)
; #define PG8_WAIT_V(n) asm volatile("s_waitcnt vmcnt(" #n ")" ::: "memory")
; #define PG8_WAIT_L(n) asm volatile("s_waitcnt lgkmcnt(" #n ")" ::: "memory")
; #define PG8_BAR __builtin_amdgcn_s_barrier()
; #define PG8_SCHED __builtin_amdgcn_sched_barrier(0)
; template <class Epi, class Sched, bool ALIGN_EPI = false, bool SP2 = false>
; __device__ __forceinline__ void gemm_phase(PG8_LAS unsigned char* lds, const Gemm g, const Sched& S, const Epi& E, const int wv) {
;     ...
;             PG8_LDA(At, 1, 1); PG8_STAGE(PG8_SB(1, 0), b3, voffB); PG8_STAGE(PG8_SB(1, 1), b3 + hstep, voffB); PG8_STAGE(PG8_SA(1, 0), a3, voffA);
;             PG8_WAIT_V(8); PG8_WAIT_L(0); PG8_BAR; PG8_MMA(1, 0, At, B0); PG8_MMA(1, 1, At, B1); PG8_BAR; PG8_SCHED;
;     ...
;         if constexpr (ALIGN_EPI) { if (wr == 0) PG8_BAR; }
	s_setprio 0
	s_add_i32 s26, s48, s36
	v_lshl_add_u64 v[180:181], v[180:181], 0, s[2:3]
	s_mov_b32 m0, s26
	ds_read_b128 v[172:175], v185 offset:49152
	ds_read_b128 v[176:179], v185 offset:50176
	ds_read_b128 v[186:189], v185 offset:51200
	ds_read_b128 v[190:193], v185 offset:52224
	ds_read_b128 v[194:197], v185 offset:53248
	ds_read_b128 v[198:201], v185 offset:54272
	ds_read_b128 v[202:205], v185 offset:55296
	ds_read_b128 v[206:209], v185 offset:56320
	global_load_lds_dwordx4 v[180:181], off
	s_add_i32 m0, s26, 0x2000
	s_add_u32 s24, s24, 0x40080
	v_lshl_add_u64 v[180:181], v[210:211], 0, s[2:3]
	s_addc_u32 s25, s25, 0
	s_add_i32 s26, s49, s36
	global_load_lds_dwordx4 v[180:181], off
	v_lshl_add_u64 v[180:181], s[24:25], 0, v[0:1]
	s_mov_b32 m0, s26
	s_nop 0
	global_load_lds_dwordx4 v[180:181], off
	v_lshl_add_u64 v[180:181], s[24:25], 0, v[158:159]
	s_add_i32 m0, s26, 0x2000
	s_nop 0
	global_load_lds_dwordx4 v[180:181], off
	v_lshl_add_u64 v[180:181], v[212:213], 0, s[2:3]
	s_mov_b32 m0, s40
	s_nop 0
	global_load_lds_dwordx4 v[180:181], off
	v_lshl_add_u64 v[180:181], v[214:215], 0, s[2:3]
	s_mov_b32 m0, s41
	s_nop 0
	global_load_lds_dwordx4 v[180:181], off
	s_waitcnt vmcnt(8)
	s_waitcnt lgkmcnt(0)
	s_setprio 1
	s_barrier
	s_waitcnt lgkmcnt(0)
	v_mfma_f32_16x16x32_bf16 v[62:65], v[114:117], v[172:175], v[62:65]
	v_mfma_f32_16x16x32_bf16 v[58:61], v[122:125], v[172:175], v[58:61]
	v_mfma_f32_16x16x32_bf16 v[46:49], v[114:117], v[186:189], v[46:49]
	v_mfma_f32_16x16x32_bf16 v[42:45], v[122:125], v[186:189], v[42:45]
	v_mfma_f32_16x16x32_bf16 v[30:33], v[114:117], v[194:197], v[30:33]
	v_mfma_f32_16x16x32_bf16 v[26:29], v[122:125], v[194:197], v[26:29]
	v_mfma_f32_16x16x32_bf16 v[14:17], v[114:117], v[202:205], v[14:17]
	v_mfma_f32_16x16x32_bf16 v[10:13], v[122:125], v[202:205], v[10:13]
	v_mfma_f32_16x16x32_bf16 v[62:65], v[118:121], v[176:179], v[62:65]
	v_mfma_f32_16x16x32_bf16 v[58:61], v[126:129], v[176:179], v[58:61]
	v_mfma_f32_16x16x32_bf16 v[46:49], v[118:121], v[190:193], v[46:49]
	v_mfma_f32_16x16x32_bf16 v[42:45], v[126:129], v[190:193], v[42:45]
	v_mfma_f32_16x16x32_bf16 v[30:33], v[118:121], v[198:201], v[30:33]
	v_mfma_f32_16x16x32_bf16 v[26:29], v[126:129], v[198:201], v[26:29]
	v_mfma_f32_16x16x32_bf16 v[14:17], v[118:121], v[206:209], v[14:17]
	v_mfma_f32_16x16x32_bf16 v[10:13], v[126:129], v[206:209], v[10:13]
	s_setprio 0
	s_setprio 1
	v_mfma_f32_16x16x32_bf16 v[54:57], v[130:133], v[172:175], v[54:57]
	v_mfma_f32_16x16x32_bf16 v[50:53], v[164:167], v[172:175], v[50:53]
	v_mfma_f32_16x16x32_bf16 v[38:41], v[130:133], v[186:189], v[38:41]
	v_mfma_f32_16x16x32_bf16 v[34:37], v[164:167], v[186:189], v[34:37]
	v_mfma_f32_16x16x32_bf16 v[22:25], v[130:133], v[194:197], v[22:25]
	v_mfma_f32_16x16x32_bf16 v[18:21], v[164:167], v[194:197], v[18:21]
	v_mfma_f32_16x16x32_bf16 v[6:9], v[130:133], v[202:205], v[6:9]
	v_mfma_f32_16x16x32_bf16 v[2:5], v[164:167], v[202:205], v[2:5]
	v_mfma_f32_16x16x32_bf16 v[54:57], v[134:137], v[176:179], v[54:57]
	v_mfma_f32_16x16x32_bf16 v[50:53], v[168:171], v[176:179], v[50:53]
	v_mfma_f32_16x16x32_bf16 v[38:41], v[134:137], v[190:193], v[38:41]
	v_mfma_f32_16x16x32_bf16 v[34:37], v[168:171], v[190:193], v[34:37]
	v_mfma_f32_16x16x32_bf16 v[22:25], v[134:137], v[198:201], v[22:25]
	v_mfma_f32_16x16x32_bf16 v[18:21], v[168:171], v[198:201], v[18:21]
	v_mfma_f32_16x16x32_bf16 v[6:9], v[134:137], v[206:209], v[6:9]
	v_mfma_f32_16x16x32_bf16 v[2:5], v[168:171], v[206:209], v[2:5]
	s_barrier
	s_setprio 0
	s_add_i32 s47, s47, 2
	s_add_u32 s22, s22, 0x100
	s_addc_u32 s23, s23, 0
	s_add_u32 s45, s45, 0x100
	s_addc_u32 s46, s46, 0
	s_cmp_gt_u32 s47, 13
	s_cbranch_scc0 .LBB0_350
	s_and_b64 vcc, exec, s[8:9]
	s_cbranch_vccz .LBB0_353
	s_barrier

; #define PG8_STAGE(bufoff, gbase, voff) do { _Pragma("unroll") for (int _i = 0; _i < 2; ++_i) \
;         __builtin_amdgcn_global_load_lds((const unsigned*)((const char*)(gbase) + (voff)[_i]), (PG8_LAS unsigned*)(lds + (bufoff) + ldsw + _i * 8192), 16, 0, 0); } while (0)
; #define PG8_LDA(dst, b, h) do { _Pragma("unroll") for (int m = 0; m < 4; ++m) _Pragma("unroll") for (int k = 0; k < 2; ++k) dst[m][k] = *(const PG8_LAS bf16x8*)(lds + PG8_SA(b, h) + aoff + m * 2048 + k * 1024); } while (0)
; #define PG8_LDB(dst, b, h) do { _Pragma("unroll") for (int n = 0; n < 2; ++n) _Pragma("unroll") for (int k = 0; k < 2; ++k) dst[n][k] = *(const PG8_LAS bf16x8*)(lds + PG8_SB(b, h) + boff + n * 2048 + k * 1024); } while (0)
; #define PG8_MMA(ai, bj, At, Bt) do { __builtin_amdgcn_s_setprio(1); _Pragma("unroll") for (int m = 0; m < 4; ++m) _Pragma("unroll") for (int n = 0; n < 2; ++n) _Pragma("unroll") for (int k = 0; k < 2; ++k) \
;         acc[ai][bj][m][n] = __builtin_amdgcn_mfma_f32_16x16x32_bf16(Bt[n][k], At[m][k], acc[ai][bj][m][n], 0, 0, 0); __builtin_amdgcn_s_setprio(0); } while (0)
; #define PG8_WAIT_V(n) asm volatile("s_waitcnt vmcnt(" #n ")" ::: "memory")
; #define PG8_WAIT_L(n) asm volatile("s_waitcnt lgkmcnt(" #n ")" ::: "memory")
; #define PG8_BAR __builtin_amdgcn_s_barrier()
; #define PG8_SCHED __builtin_amdgcn_sched_barrier(0)
; template <class Epi, class Sched, bool ALIGN_EPI = false, bool SP2 = false>
; __device__ __forceinline__ void gemm_phase(PG8_LAS unsigned char* lds, const Gemm g, const Sched& S, const Epi& E, const int wv) {
;     ...
;             const bool last = (t == nt - 2);
;             const char* a1 = cA + (size_t)(t + 1) * kstep;
;             const char* a2 = last ? nA : cA + (size_t)(t + 2) * kstep; const char* b2 = last ? nB : cB + (size_t)(t + 2) * kstep;
;             const char* a3 = a2 + kstep; const char* b3 = b2 + kstep;
;             if (last && has_next) S.a_ready(nxt);
;             if constexpr (SP2) {
;             PG8_LDB(B0, 0, 0); PG8_LDB(B1, 0, 1); PG8_SCHED; PG8_LDA(At, 0, 0); PG8_STAGE(PG8_SA(1, 1), a1 + hstep, voffA);
;             PG8_WAIT_V(8); PG8_WAIT_L(0); PG8_BAR; PG8_MMA(0, 0, At, B0); PG8_MMA(0, 1, At, B1); PG8_BAR; PG8_SCHED;
;             PG8_LDA(At, 0, 1); PG8_STAGE(PG8_SB(0, 0), b2, voffB); PG8_STAGE(PG8_SB(0, 1), b2 + hstep, voffB); PG8_STAGE(PG8_SA(0, 0), a2, voffA);
.LBB0_428:
	s_add_u32 s20, s18, 0xfffc0080
	s_addc_u32 s21, s19, -1
	s_add_i32 s46, 0, 0x10000
	s_cmp_eq_u32 s45, 12
	s_cselect_b32 s23, s11, s21
	s_cselect_b32 s22, s33, s20
	s_cselect_b32 s21, s9, s44
	s_cselect_b32 s20, s42, s43
	s_add_i32 s48, 0, 0x14000
	v_add_u32_e32 v152, s46, v166
	v_add_u32_e32 v164, s48, v166
	ds_read_b128 v[140:143], v152
	ds_read_b128 v[144:147], v152 offset:1024
	ds_read_b128 v[148:151], v152 offset:2048
	ds_read_b128 v[152:155], v152 offset:3072
	ds_read_b128 v[156:159], v164
	ds_read_b128 v[160:163], v164 offset:1024
	ds_read_b128 v[170:173], v164 offset:2048
	ds_read_b128 v[174:177], v164 offset:3072
	v_lshl_add_u64 v[210:211], s[18:19], 0, v[136:137]
	s_add_i32 m0, s30, 0xc000
	ds_read_b128 v[178:181], v168
	ds_read_b128 v[182:185], v168 offset:1024
	ds_read_b128 v[186:189], v168 offset:2048
	ds_read_b128 v[190:193], v168 offset:3072
	ds_read_b128 v[194:197], v168 offset:4096
	ds_read_b128 v[198:201], v168 offset:5120
	ds_read_b128 v[202:205], v168 offset:6144
	ds_read_b128 v[206:209], v168 offset:7168
	global_load_lds_dwordx4 v[210:211], off
	v_lshl_add_u64 v[210:211], s[18:19], 0, v[138:139]
	s_add_i32 m0, s30, 0xe000
	s_nop 0
	global_load_lds_dwordx4 v[210:211], off
	s_waitcnt vmcnt(8)
	s_waitcnt lgkmcnt(0)
	s_setprio 1
	s_barrier
	s_waitcnt lgkmcnt(0)
	v_mfma_f32_16x16x32_bf16 v[126:129], v[140:143], v[178:181], v[126:129]
	v_mfma_f32_16x16x32_bf16 v[118:121], v[148:151], v[178:181], v[118:121]
	v_mfma_f32_16x16x32_bf16 v[110:113], v[140:143], v[186:189], v[110:113]
	v_mfma_f32_16x16x32_bf16 v[102:105], v[148:151], v[186:189], v[102:105]
	v_mfma_f32_16x16x32_bf16 v[94:97], v[140:143], v[194:197], v[94:97]
	v_mfma_f32_16x16x32_bf16 v[86:89], v[148:151], v[194:197], v[86:89]
	v_mfma_f32_16x16x32_bf16 v[78:81], v[140:143], v[202:205], v[78:81]
	v_mfma_f32_16x16x32_bf16 v[70:73], v[148:151], v[202:205], v[70:73]
	v_mfma_f32_16x16x32_bf16 v[126:129], v[144:147], v[182:185], v[126:129]
	v_mfma_f32_16x16x32_bf16 v[118:121], v[152:155], v[182:185], v[118:121]
	v_mfma_f32_16x16x32_bf16 v[110:113], v[144:147], v[190:193], v[110:113]
	v_mfma_f32_16x16x32_bf16 v[102:105], v[152:155], v[190:193], v[102:105]
	v_mfma_f32_16x16x32_bf16 v[94:97], v[144:147], v[198:201], v[94:97]
	v_mfma_f32_16x16x32_bf16 v[86:89], v[152:155], v[198:201], v[86:89]
	v_mfma_f32_16x16x32_bf16 v[78:81], v[144:147], v[206:209], v[78:81]
	v_mfma_f32_16x16x32_bf16 v[70:73], v[152:155], v[206:209], v[70:73]
	s_setprio 0
	s_setprio 1
	v_mfma_f32_16x16x32_bf16 v[122:125], v[156:159], v[178:181], v[122:125]
	v_mfma_f32_16x16x32_bf16 v[114:117], v[170:173], v[178:181], v[114:117]
	v_mfma_f32_16x16x32_bf16 v[106:109], v[156:159], v[186:189], v[106:109]
	v_mfma_f32_16x16x32_bf16 v[98:101], v[170:173], v[186:189], v[98:101]
	v_mfma_f32_16x16x32_bf16 v[90:93], v[156:159], v[194:197], v[90:93]
	v_mfma_f32_16x16x32_bf16 v[82:85], v[170:173], v[194:197], v[82:85]
	v_mfma_f32_16x16x32_bf16 v[74:77], v[156:159], v[202:205], v[74:77]
	v_mfma_f32_16x16x32_bf16 v[66:69], v[170:173], v[202:205], v[66:69]
	v_mfma_f32_16x16x32_bf16 v[122:125], v[160:163], v[182:185], v[122:125]
	v_mfma_f32_16x16x32_bf16 v[114:117], v[174:177], v[182:185], v[114:117]
	v_mfma_f32_16x16x32_bf16 v[106:109], v[160:163], v[190:193], v[106:109]
	v_mfma_f32_16x16x32_bf16 v[98:101], v[174:177], v[190:193], v[98:101]
	v_mfma_f32_16x16x32_bf16 v[90:93], v[160:163], v[198:201], v[90:93]
	v_mfma_f32_16x16x32_bf16 v[82:85], v[174:177], v[198:201], v[82:85]
	v_mfma_f32_16x16x32_bf16 v[74:77], v[160:163], v[206:209], v[74:77]
	v_mfma_f32_16x16x32_bf16 v[66:69], v[174:177], v[206:209], v[66:69]
	s_barrier
	s_setprio 0
	s_add_i32 s46, s46, s29
	v_lshl_add_u64 v[210:211], s[20:21], 0, v[0:1]
	s_mov_b32 m0, s46
	ds_read_b128 v[178:181], v168 offset:16384
	ds_read_b128 v[182:185], v168 offset:17408
	ds_read_b128 v[186:189], v168 offset:18432
	ds_read_b128 v[190:193], v168 offset:19456
	ds_read_b128 v[194:197], v168 offset:20480
	ds_read_b128 v[198:201], v168 offset:21504
	ds_read_b128 v[202:205], v168 offset:22528
	ds_read_b128 v[206:209], v168 offset:23552
	global_load_lds_dwordx4 v[210:211], off
	s_add_i32 m0, s46, 0x2000
	s_add_u32 s46, s20, 0x40000
	v_lshl_add_u64 v[212:213], s[20:21], 0, v[130:131]
	s_addc_u32 s47, s21, 0
	s_add_i32 s48, s48, s29
	global_load_lds_dwordx4 v[212:213], off
	v_lshl_add_u64 v[214:215], s[46:47], 0, v[0:1]
	s_mov_b32 m0, s48
	v_lshl_add_u64 v[216:217], s[22:23], 0, v[132:133]
	global_load_lds_dwordx4 v[214:215], off
	v_lshl_add_u64 v[214:215], s[46:47], 0, v[130:131]
	s_add_i32 m0, s48, 0x2000
	s_nop 0
	global_load_lds_dwordx4 v[214:215], off
	v_lshl_add_u64 v[214:215], s[22:23], 0, v[134:135]
	s_mov_b32 m0, s30
	s_nop 0
	global_load_lds_dwordx4 v[214:215], off
	s_mov_b32 m0, s31
	s_nop 0
	global_load_lds_dwordx4 v[216:217], off
	s_waitcnt vmcnt(8)
	s_waitcnt lgkmcnt(0)
	s_setprio 1
	s_barrier
; #define PG8_STAGE(bufoff, gbase, voff) do { _Pragma("unroll") for (int _i = 0; _i < 2; ++_i) \
;         __builtin_amdgcn_global_load_lds((const unsigned*)((const char*)(gbase) + (voff)[_i]), (PG8_LAS unsigned*)(lds + (bufoff) + ldsw + _i * 8192), 16, 0, 0); } while (0)
; #define PG8_LDA(dst, b, h) do { _Pragma("unroll") for (int m = 0; m < 4; ++m) _Pragma("unroll") for (int k = 0; k < 2; ++k) dst[m][k] = *(const PG8_LAS bf16x8*)(lds + PG8_SA(b, h) + aoff + m * 2048 + k * 1024); } while (0)
; #define PG8_LDB(dst, b, h) do { _Pragma("unroll") for (int n = 0; n < 2; ++n) _Pragma("unroll") for (int k = 0; k < 2; ++k) dst[n][k] = *(const PG8_LAS bf16x8*)(lds + PG8_SB(b, h) + boff + n * 2048 + k * 1024); } while (0)
; #define PG8_MMA(ai, bj, At, Bt) do { __builtin_amdgcn_s_setprio(1); _Pragma("unroll") for (int m = 0; m < 4; ++m) _Pragma("unroll") for (int n = 0; n < 2; ++n) _Pragma("unroll") for (int k = 0; k < 2; ++k) \
;         acc[ai][bj][m][n] = __builtin_amdgcn_mfma_f32_16x16x32_bf16(Bt[n][k], At[m][k], acc[ai][bj][m][n], 0, 0, 0); __builtin_amdgcn_s_setprio(0); } while (0)
; #define PG8_WAIT_V(n) asm volatile("s_waitcnt vmcnt(" #n ")" ::: "memory")
; #define PG8_WAIT_L(n) asm volatile("s_waitcnt lgkmcnt(" #n ")" ::: "memory")
; #define PG8_BAR __builtin_amdgcn_s_barrier()
; #define PG8_SCHED __builtin_amdgcn_sched_barrier(0)
; template <class Epi, class Sched, bool ALIGN_EPI = false, bool SP2 = false>
; __device__ __forceinline__ void gemm_phase(PG8_LAS unsigned char* lds, const Gemm g, const Sched& S, const Epi& E, const int wv) {
;     ...
;             PG8_WAIT_V(8); PG8_WAIT_L(0); PG8_BAR; PG8_MMA(1, 0, At, B0); PG8_MMA(1, 1, At, B1); PG8_BAR; PG8_SCHED;
;             PG8_LDB(B0, 1, 0); PG8_LDB(B1, 1, 1); PG8_SCHED; PG8_LDA(At, 1, 0); PG8_STAGE(PG8_SA(0, 1), a2 + hstep, voffA);
;             PG8_WAIT_V(8); PG8_WAIT_L(0); PG8_BAR; PG8_MMA(0, 0, At, B0); PG8_MMA(0, 1, At, B1); PG8_BAR; PG8_SCHED;
	s_waitcnt lgkmcnt(0)
	v_mfma_f32_16x16x32_bf16 v[62:65], v[140:143], v[178:181], v[62:65]
	v_mfma_f32_16x16x32_bf16 v[54:57], v[148:151], v[178:181], v[54:57]
	v_mfma_f32_16x16x32_bf16 v[46:49], v[140:143], v[186:189], v[46:49]
	v_mfma_f32_16x16x32_bf16 v[38:41], v[148:151], v[186:189], v[38:41]
	v_mfma_f32_16x16x32_bf16 v[30:33], v[140:143], v[194:197], v[30:33]
	v_mfma_f32_16x16x32_bf16 v[22:25], v[148:151], v[194:197], v[22:25]
	v_mfma_f32_16x16x32_bf16 v[14:17], v[140:143], v[202:205], v[14:17]
	v_mfma_f32_16x16x32_bf16 v[6:9], v[148:151], v[202:205], v[6:9]
	v_mfma_f32_16x16x32_bf16 v[62:65], v[144:147], v[182:185], v[62:65]
	v_mfma_f32_16x16x32_bf16 v[54:57], v[152:155], v[182:185], v[54:57]
	v_mfma_f32_16x16x32_bf16 v[46:49], v[144:147], v[190:193], v[46:49]
	v_mfma_f32_16x16x32_bf16 v[38:41], v[152:155], v[190:193], v[38:41]
	v_mfma_f32_16x16x32_bf16 v[30:33], v[144:147], v[198:201], v[30:33]
	v_mfma_f32_16x16x32_bf16 v[22:25], v[152:155], v[198:201], v[22:25]
	v_mfma_f32_16x16x32_bf16 v[14:17], v[144:147], v[206:209], v[14:17]
	v_mfma_f32_16x16x32_bf16 v[6:9], v[152:155], v[206:209], v[6:9]
	s_setprio 0
	s_setprio 1
	v_mfma_f32_16x16x32_bf16 v[58:61], v[156:159], v[178:181], v[58:61]
	v_mfma_f32_16x16x32_bf16 v[50:53], v[170:173], v[178:181], v[50:53]
	v_mfma_f32_16x16x32_bf16 v[42:45], v[156:159], v[186:189], v[42:45]
	v_mfma_f32_16x16x32_bf16 v[34:37], v[170:173], v[186:189], v[34:37]
	v_mfma_f32_16x16x32_bf16 v[26:29], v[156:159], v[194:197], v[26:29]
	v_mfma_f32_16x16x32_bf16 v[18:21], v[170:173], v[194:197], v[18:21]
	v_mfma_f32_16x16x32_bf16 v[10:13], v[156:159], v[202:205], v[10:13]
	v_mfma_f32_16x16x32_bf16 v[2:5], v[170:173], v[202:205], v[2:5]
	v_mfma_f32_16x16x32_bf16 v[58:61], v[160:163], v[182:185], v[58:61]
	v_mfma_f32_16x16x32_bf16 v[50:53], v[174:177], v[182:185], v[50:53]
	v_mfma_f32_16x16x32_bf16 v[42:45], v[160:163], v[190:193], v[42:45]
	v_mfma_f32_16x16x32_bf16 v[34:37], v[174:177], v[190:193], v[34:37]
	v_mfma_f32_16x16x32_bf16 v[26:29], v[160:163], v[198:201], v[26:29]
	v_mfma_f32_16x16x32_bf16 v[18:21], v[174:177], v[198:201], v[18:21]
	v_mfma_f32_16x16x32_bf16 v[10:13], v[160:163], v[206:209], v[10:13]
	v_mfma_f32_16x16x32_bf16 v[2:5], v[174:177], v[206:209], v[2:5]
	s_barrier
	s_setprio 0
	s_add_i32 s46, 0, 0x18000
	s_add_i32 s47, 0, 0x1c000
	v_add_u32_e32 v152, s46, v166
	v_add_u32_e32 v164, s47, v166
	ds_read_b128 v[140:143], v152
	ds_read_b128 v[144:147], v152 offset:1024
	ds_read_b128 v[148:151], v152 offset:2048
	ds_read_b128 v[152:155], v152 offset:3072
	ds_read_b128 v[156:159], v164
	ds_read_b128 v[160:163], v164 offset:1024
	ds_read_b128 v[170:173], v164 offset:2048
	ds_read_b128 v[174:177], v164 offset:3072
	s_add_u32 s22, s22, 0x40000
	s_addc_u32 s23, s23, 0
	s_mov_b32 m0, s36
	v_lshl_add_u64 v[218:219], s[22:23], 0, v[134:135]
	ds_read_b128 v[178:181], v168 offset:32768
	ds_read_b128 v[182:185], v168 offset:33792
	ds_read_b128 v[186:189], v168 offset:34816
	ds_read_b128 v[190:193], v168 offset:35840
	ds_read_b128 v[194:197], v168 offset:36864
	ds_read_b128 v[198:201], v168 offset:37888
	ds_read_b128 v[202:205], v168 offset:38912
	ds_read_b128 v[206:209], v168 offset:39936
	global_load_lds_dwordx4 v[218:219], off
	v_lshl_add_u64 v[218:219], s[22:23], 0, v[132:133]
	s_mov_b32 m0, s37
	s_nop 0
	global_load_lds_dwordx4 v[218:219], off
	s_waitcnt vmcnt(8)
	s_waitcnt lgkmcnt(0)
	s_setprio 1
	s_barrier
	s_waitcnt lgkmcnt(0)
	v_mfma_f32_16x16x32_bf16 v[126:129], v[140:143], v[178:181], v[126:129]
	v_mfma_f32_16x16x32_bf16 v[118:121], v[148:151], v[178:181], v[118:121]
	v_mfma_f32_16x16x32_bf16 v[110:113], v[140:143], v[186:189], v[110:113]
	v_mfma_f32_16x16x32_bf16 v[102:105], v[148:151], v[186:189], v[102:105]
	v_mfma_f32_16x16x32_bf16 v[94:97], v[140:143], v[194:197], v[94:97]
	v_mfma_f32_16x16x32_bf16 v[86:89], v[148:151], v[194:197], v[86:89]
	v_mfma_f32_16x16x32_bf16 v[78:81], v[140:143], v[202:205], v[78:81]
	v_mfma_f32_16x16x32_bf16 v[70:73], v[148:151], v[202:205], v[70:73]
	v_mfma_f32_16x16x32_bf16 v[126:129], v[144:147], v[182:185], v[126:129]
	v_mfma_f32_16x16x32_bf16 v[118:121], v[152:155], v[182:185], v[118:121]
	v_mfma_f32_16x16x32_bf16 v[110:113], v[144:147], v[190:193], v[110:113]
	v_mfma_f32_16x16x32_bf16 v[102:105], v[152:155], v[190:193], v[102:105]
	v_mfma_f32_16x16x32_bf16 v[94:97], v[144:147], v[198:201], v[94:97]
	v_mfma_f32_16x16x32_bf16 v[86:89], v[152:155], v[198:201], v[86:89]
	v_mfma_f32_16x16x32_bf16 v[78:81], v[144:147], v[206:209], v[78:81]
	v_mfma_f32_16x16x32_bf16 v[70:73], v[152:155], v[206:209], v[70:73]
	s_setprio 0
	s_setprio 1
	v_mfma_f32_16x16x32_bf16 v[122:125], v[156:159], v[178:181], v[122:125]
	v_mfma_f32_16x16x32_bf16 v[114:117], v[170:173], v[178:181], v[114:117]
	v_mfma_f32_16x16x32_bf16 v[106:109], v[156:159], v[186:189], v[106:109]
	v_mfma_f32_16x16x32_bf16 v[98:101], v[170:173], v[186:189], v[98:101]
	v_mfma_f32_16x16x32_bf16 v[90:93], v[156:159], v[194:197], v[90:93]
	v_mfma_f32_16x16x32_bf16 v[82:85], v[170:173], v[194:197], v[82:85]
	v_mfma_f32_16x16x32_bf16 v[74:77], v[156:159], v[202:205], v[74:77]
	v_mfma_f32_16x16x32_bf16 v[66:69], v[170:173], v[202:205], v[66:69]
	v_mfma_f32_16x16x32_bf16 v[122:125], v[160:163], v[182:185], v[122:125]
	v_mfma_f32_16x16x32_bf16 v[114:117], v[174:177], v[182:185], v[114:117]
	v_mfma_f32_16x16x32_bf16 v[106:109], v[160:163], v[190:193], v[106:109]
	v_mfma_f32_16x16x32_bf16 v[98:101], v[174:177], v[190:193], v[98:101]
	v_mfma_f32_16x16x32_bf16 v[90:93], v[160:163], v[198:201], v[90:93]
	v_mfma_f32_16x16x32_bf16 v[82:85], v[174:177], v[198:201], v[82:85]
	v_mfma_f32_16x16x32_bf16 v[74:77], v[160:163], v[206:209], v[74:77]
	v_mfma_f32_16x16x32_bf16 v[66:69], v[174:177], v[206:209], v[66:69]
	s_barrier
; #define PG8_STAGE(bufoff, gbase, voff) do { _Pragma("unroll") for (int _i = 0; _i < 2; ++_i) \
;         __builtin_amdgcn_global_load_lds((const unsigned*)((const char*)(gbase) + (voff)[_i]), (PG8_LAS unsigned*)(lds + (bufoff) + ldsw + _i * 8192), 16, 0, 0); } while (0)
; #define PG8_LDA(dst, b, h) do { _Pragma("unroll") for (int m = 0; m < 4; ++m) _Pragma("unroll") for (int k = 0; k < 2; ++k) dst[m][k] = *(const PG8_LAS bf16x8*)(lds + PG8_SA(b, h) + aoff + m * 2048 + k * 1024); } while (0)
; #define PG8_MMA(ai, bj, At, Bt) do { __builtin_amdgcn_s_setprio(1); _Pragma("unroll") for (int m = 0; m < 4; ++m) _Pragma("unroll") for (int n = 0; n < 2; ++n) _Pragma("unroll") for (int k = 0; k < 2; ++k) \
;         acc[ai][bj][m][n] = __builtin_amdgcn_mfma_f32_16x16x32_bf16(Bt[n][k], At[m][k], acc[ai][bj][m][n], 0, 0, 0); __builtin_amdgcn_s_setprio(0); } while (0)
; #define PG8_WAIT_V(n) asm volatile("s_waitcnt vmcnt(" #n ")" ::: "memory")
; #define PG8_WAIT_L(n) asm volatile("s_waitcnt lgkmcnt(" #n ")" ::: "memory")
; #define PG8_BAR __builtin_amdgcn_s_barrier()
; #define PG8_SCHED __builtin_amdgcn_sched_barrier(0)
; template <class Epi, class Sched, bool ALIGN_EPI = false, bool SP2 = false>
; __device__ __forceinline__ void gemm_phase(PG8_LAS unsigned char* lds, const Gemm g, const Sched& S, const Epi& E, const int wv) {
;     ...
;             PG8_LDA(At, 1, 1); PG8_STAGE(PG8_SB(1, 0), b3, voffB); PG8_STAGE(PG8_SB(1, 1), b3 + hstep, voffB); PG8_STAGE(PG8_SA(1, 0), a3, voffA);
;             PG8_WAIT_V(8); PG8_WAIT_L(0); PG8_BAR; PG8_MMA(1, 0, At, B0); PG8_MMA(1, 1, At, B1); PG8_BAR; PG8_SCHED;
;     ...
;         if constexpr (ALIGN_EPI) { if (wr == 0) PG8_BAR; }
	s_setprio 0
	s_add_i32 s22, s46, s29
	v_lshl_add_u64 v[210:211], v[210:211], 0, s[2:3]
	s_mov_b32 m0, s22
	ds_read_b128 v[178:181], v168 offset:49152
	ds_read_b128 v[182:185], v168 offset:50176
	ds_read_b128 v[186:189], v168 offset:51200
	ds_read_b128 v[190:193], v168 offset:52224
	ds_read_b128 v[194:197], v168 offset:53248
	ds_read_b128 v[198:201], v168 offset:54272
	ds_read_b128 v[202:205], v168 offset:55296
	ds_read_b128 v[206:209], v168 offset:56320
	global_load_lds_dwordx4 v[210:211], off
	s_add_i32 m0, s22, 0x2000
	s_add_u32 s20, s20, 0x40080
	v_lshl_add_u64 v[210:211], v[212:213], 0, s[2:3]
	s_addc_u32 s21, s21, 0
	s_add_i32 s22, s47, s29
	global_load_lds_dwordx4 v[210:211], off
	v_lshl_add_u64 v[210:211], s[20:21], 0, v[0:1]
	s_mov_b32 m0, s22
	s_nop 0
	global_load_lds_dwordx4 v[210:211], off
	v_lshl_add_u64 v[210:211], s[20:21], 0, v[130:131]
	s_add_i32 m0, s22, 0x2000
	s_nop 0
	global_load_lds_dwordx4 v[210:211], off
	v_lshl_add_u64 v[210:211], v[214:215], 0, s[2:3]
	s_mov_b32 m0, s39
	s_nop 0
	global_load_lds_dwordx4 v[210:211], off
	v_lshl_add_u64 v[210:211], v[216:217], 0, s[2:3]
	s_mov_b32 m0, s40
	s_nop 0
	global_load_lds_dwordx4 v[210:211], off
	s_waitcnt vmcnt(8)
	s_waitcnt lgkmcnt(0)
	s_setprio 1
	s_barrier
	s_waitcnt lgkmcnt(0)
	v_mfma_f32_16x16x32_bf16 v[62:65], v[140:143], v[178:181], v[62:65]
	v_mfma_f32_16x16x32_bf16 v[54:57], v[148:151], v[178:181], v[54:57]
	v_mfma_f32_16x16x32_bf16 v[46:49], v[140:143], v[186:189], v[46:49]
	v_mfma_f32_16x16x32_bf16 v[38:41], v[148:151], v[186:189], v[38:41]
	v_mfma_f32_16x16x32_bf16 v[30:33], v[140:143], v[194:197], v[30:33]
	v_mfma_f32_16x16x32_bf16 v[22:25], v[148:151], v[194:197], v[22:25]
	v_mfma_f32_16x16x32_bf16 v[14:17], v[140:143], v[202:205], v[14:17]
	v_mfma_f32_16x16x32_bf16 v[6:9], v[148:151], v[202:205], v[6:9]
	v_mfma_f32_16x16x32_bf16 v[62:65], v[144:147], v[182:185], v[62:65]
	v_mfma_f32_16x16x32_bf16 v[54:57], v[152:155], v[182:185], v[54:57]
	v_mfma_f32_16x16x32_bf16 v[46:49], v[144:147], v[190:193], v[46:49]
	v_mfma_f32_16x16x32_bf16 v[38:41], v[152:155], v[190:193], v[38:41]
	v_mfma_f32_16x16x32_bf16 v[30:33], v[144:147], v[198:201], v[30:33]
	v_mfma_f32_16x16x32_bf16 v[22:25], v[152:155], v[198:201], v[22:25]
	v_mfma_f32_16x16x32_bf16 v[14:17], v[144:147], v[206:209], v[14:17]
	v_mfma_f32_16x16x32_bf16 v[6:9], v[152:155], v[206:209], v[6:9]
	s_setprio 0
	s_setprio 1
	v_mfma_f32_16x16x32_bf16 v[58:61], v[156:159], v[178:181], v[58:61]
	v_mfma_f32_16x16x32_bf16 v[50:53], v[170:173], v[178:181], v[50:53]
	v_mfma_f32_16x16x32_bf16 v[42:45], v[156:159], v[186:189], v[42:45]
	v_mfma_f32_16x16x32_bf16 v[34:37], v[170:173], v[186:189], v[34:37]
	v_mfma_f32_16x16x32_bf16 v[26:29], v[156:159], v[194:197], v[26:29]
	v_mfma_f32_16x16x32_bf16 v[18:21], v[170:173], v[194:197], v[18:21]
	v_mfma_f32_16x16x32_bf16 v[10:13], v[156:159], v[202:205], v[10:13]
	v_mfma_f32_16x16x32_bf16 v[2:5], v[170:173], v[202:205], v[2:5]
	v_mfma_f32_16x16x32_bf16 v[58:61], v[160:163], v[182:185], v[58:61]
	v_mfma_f32_16x16x32_bf16 v[50:53], v[174:177], v[182:185], v[50:53]
	v_mfma_f32_16x16x32_bf16 v[42:45], v[160:163], v[190:193], v[42:45]
	v_mfma_f32_16x16x32_bf16 v[34:37], v[174:177], v[190:193], v[34:37]
	v_mfma_f32_16x16x32_bf16 v[26:29], v[160:163], v[198:201], v[26:29]
	v_mfma_f32_16x16x32_bf16 v[18:21], v[174:177], v[198:201], v[18:21]
	v_mfma_f32_16x16x32_bf16 v[10:13], v[160:163], v[206:209], v[10:13]
	v_mfma_f32_16x16x32_bf16 v[2:5], v[174:177], v[206:209], v[2:5]
	s_barrier
	s_setprio 0
	s_add_i32 s45, s45, 2
	s_add_u32 s18, s18, 0x100
	s_addc_u32 s19, s19, 0
	s_add_u32 s43, s43, 0x100
	s_addc_u32 s44, s44, 0
	s_cmp_gt_u32 s45, 13
	s_cbranch_scc0 .LBB0_428
	s_and_b64 vcc, exec, s[6:7]
	s_cbranch_vccz .LBB0_431
	s_barrier

; #define PG8_STAGE(bufoff, gbase, voff) do { _Pragma("unroll") for (int _i = 0; _i < 2; ++_i) \
;         __builtin_amdgcn_global_load_lds((const unsigned*)((const char*)(gbase) + (voff)[_i]), (PG8_LAS unsigned*)(lds + (bufoff) + ldsw + _i * 8192), 16, 0, 0); } while (0)
; #define PG8_LDA(dst, b, h) do { _Pragma("unroll") for (int m = 0; m < 4; ++m) _Pragma("unroll") for (int k = 0; k < 2; ++k) dst[m][k] = *(const PG8_LAS bf16x8*)(lds + PG8_SA(b, h) + aoff + m * 2048 + k * 1024); } while (0)
; #define PG8_LDB(dst, b, h) do { _Pragma("unroll") for (int n = 0; n < 2; ++n) _Pragma("unroll") for (int k = 0; k < 2; ++k) dst[n][k] = *(const PG8_LAS bf16x8*)(lds + PG8_SB(b, h) + boff + n * 2048 + k * 1024); } while (0)
; #define PG8_MMA(ai, bj, At, Bt) do { __builtin_amdgcn_s_setprio(1); _Pragma("unroll") for (int m = 0; m < 4; ++m) _Pragma("unroll") for (int n = 0; n < 2; ++n) _Pragma("unroll") for (int k = 0; k < 2; ++k) \
;         acc[ai][bj][m][n] = __builtin_amdgcn_mfma_f32_16x16x32_bf16(Bt[n][k], At[m][k], acc[ai][bj][m][n], 0, 0, 0); __builtin_amdgcn_s_setprio(0); } while (0)
; #define PG8_WAIT_V(n) asm volatile("s_waitcnt vmcnt(" #n ")" ::: "memory")
; #define PG8_WAIT_L(n) asm volatile("s_waitcnt lgkmcnt(" #n ")" ::: "memory")
; #define PG8_BAR __builtin_amdgcn_s_barrier()
; #define PG8_SCHED __builtin_amdgcn_sched_barrier(0)
; template <class Epi, class Sched, bool ALIGN_EPI = false, bool SP2 = false>
; __device__ __forceinline__ void gemm_phase(PG8_LAS unsigned char* lds, const Gemm g, const Sched& S, const Epi& E, const int wv) {
;     ...
;             const bool last = (t == nt - 2);
;             const char* a1 = cA + (size_t)(t + 1) * kstep;
;             const char* a2 = last ? nA : cA + (size_t)(t + 2) * kstep; const char* b2 = last ? nB : cB + (size_t)(t + 2) * kstep;
;             const char* a3 = a2 + kstep; const char* b3 = b2 + kstep;
;             if (last && has_next) S.a_ready(nxt);
;             if constexpr (SP2) {
;             PG8_LDB(B0, 0, 0); PG8_LDB(B1, 0, 1); PG8_SCHED; PG8_LDA(At, 0, 0); PG8_STAGE(PG8_SA(1, 1), a1 + hstep, voffA);
;             PG8_WAIT_V(8); PG8_WAIT_L(0); PG8_BAR; PG8_MMA(0, 0, At, B0); PG8_MMA(0, 1, At, B1); PG8_BAR; PG8_SCHED;
;             PG8_LDA(At, 0, 1); PG8_STAGE(PG8_SB(0, 0), b2, voffB); PG8_STAGE(PG8_SB(0, 1), b2 + hstep, voffB); PG8_STAGE(PG8_SA(0, 0), a2, voffA);
.LBB0_504:
	s_add_u32 s10, s8, 0x100
	s_addc_u32 s11, s9, 0
	s_add_i32 s52, 0, 0x10000
	s_cmp_eq_u32 s51, 40
	s_cselect_b32 s29, s1, s11
	s_cselect_b32 s28, s0, s10
	s_cselect_b32 s27, s25, s50
	s_cselect_b32 s26, s24, s49
	s_add_i32 s53, 0, 0x14000
	v_add_u32_e32 v142, s52, v187
	v_add_u32_e32 v168, s53, v187
	ds_read_b128 v[122:125], v142
	ds_read_b128 v[130:133], v142 offset:1024
	ds_read_b128 v[138:141], v142 offset:2048
	ds_read_b128 v[142:145], v142 offset:3072
	ds_read_b128 v[146:149], v168
	ds_read_b128 v[150:153], v168 offset:1024
	ds_read_b128 v[154:157], v168 offset:2048
	ds_read_b128 v[168:171], v168 offset:3072
	v_lshl_add_u64 v[184:185], s[8:9], 0, v[164:165]
	s_add_i32 m0, s37, 0xc000
	ds_read_b128 v[172:175], v189
	ds_read_b128 v[176:179], v189 offset:1024
	ds_read_b128 v[180:183], v189 offset:2048
	ds_read_b128 v[190:193], v189 offset:3072
	ds_read_b128 v[194:197], v189 offset:4096
	ds_read_b128 v[198:201], v189 offset:5120
	ds_read_b128 v[202:205], v189 offset:6144
	ds_read_b128 v[206:209], v189 offset:7168
	global_load_lds_dwordx4 v[184:185], off
	v_lshl_add_u64 v[184:185], s[8:9], 0, v[166:167]
	s_add_i32 m0, s37, 0xe000
	s_nop 0
	global_load_lds_dwordx4 v[184:185], off
	s_waitcnt vmcnt(8)
	s_waitcnt lgkmcnt(0)
	s_setprio 1
	s_barrier
	s_waitcnt lgkmcnt(0)
	v_mfma_f32_16x16x32_bf16 v[134:137], v[122:125], v[172:175], v[134:137]
	v_mfma_f32_16x16x32_bf16 v[126:129], v[138:141], v[172:175], v[126:129]
	v_mfma_f32_16x16x32_bf16 v[110:113], v[122:125], v[180:183], v[110:113]
	v_mfma_f32_16x16x32_bf16 v[106:109], v[138:141], v[180:183], v[106:109]
	v_mfma_f32_16x16x32_bf16 v[94:97], v[122:125], v[194:197], v[94:97]
	v_mfma_f32_16x16x32_bf16 v[90:93], v[138:141], v[194:197], v[90:93]
	v_mfma_f32_16x16x32_bf16 v[78:81], v[122:125], v[202:205], v[78:81]
	v_mfma_f32_16x16x32_bf16 v[74:77], v[138:141], v[202:205], v[74:77]
	v_mfma_f32_16x16x32_bf16 v[134:137], v[130:133], v[176:179], v[134:137]
	v_mfma_f32_16x16x32_bf16 v[126:129], v[142:145], v[176:179], v[126:129]
	v_mfma_f32_16x16x32_bf16 v[110:113], v[130:133], v[190:193], v[110:113]
	v_mfma_f32_16x16x32_bf16 v[106:109], v[142:145], v[190:193], v[106:109]
	v_mfma_f32_16x16x32_bf16 v[94:97], v[130:133], v[198:201], v[94:97]
	v_mfma_f32_16x16x32_bf16 v[90:93], v[142:145], v[198:201], v[90:93]
	v_mfma_f32_16x16x32_bf16 v[78:81], v[130:133], v[206:209], v[78:81]
	v_mfma_f32_16x16x32_bf16 v[74:77], v[142:145], v[206:209], v[74:77]
	s_setprio 0
	s_setprio 1
	v_mfma_f32_16x16x32_bf16 v[118:121], v[146:149], v[172:175], v[118:121]
	v_mfma_f32_16x16x32_bf16 v[114:117], v[154:157], v[172:175], v[114:117]
	v_mfma_f32_16x16x32_bf16 v[102:105], v[146:149], v[180:183], v[102:105]
	v_mfma_f32_16x16x32_bf16 v[98:101], v[154:157], v[180:183], v[98:101]
	v_mfma_f32_16x16x32_bf16 v[86:89], v[146:149], v[194:197], v[86:89]
	v_mfma_f32_16x16x32_bf16 v[82:85], v[154:157], v[194:197], v[82:85]
	v_mfma_f32_16x16x32_bf16 v[70:73], v[146:149], v[202:205], v[70:73]
	v_mfma_f32_16x16x32_bf16 v[66:69], v[154:157], v[202:205], v[66:69]
	v_mfma_f32_16x16x32_bf16 v[118:121], v[150:153], v[176:179], v[118:121]
	v_mfma_f32_16x16x32_bf16 v[114:117], v[168:171], v[176:179], v[114:117]
	v_mfma_f32_16x16x32_bf16 v[102:105], v[150:153], v[190:193], v[102:105]
	v_mfma_f32_16x16x32_bf16 v[98:101], v[168:171], v[190:193], v[98:101]
	v_mfma_f32_16x16x32_bf16 v[86:89], v[150:153], v[198:201], v[86:89]
	v_mfma_f32_16x16x32_bf16 v[82:85], v[168:171], v[198:201], v[82:85]
	v_mfma_f32_16x16x32_bf16 v[70:73], v[150:153], v[206:209], v[70:73]
	v_mfma_f32_16x16x32_bf16 v[66:69], v[168:171], v[206:209], v[66:69]
	s_barrier
	s_setprio 0
	s_add_i32 s8, s52, s36
	v_lshl_add_u64 v[184:185], s[26:27], 0, v[0:1]
	s_mov_b32 m0, s8
	ds_read_b128 v[172:175], v189 offset:16384
	ds_read_b128 v[176:179], v189 offset:17408
	ds_read_b128 v[180:183], v189 offset:18432
	ds_read_b128 v[190:193], v189 offset:19456
	ds_read_b128 v[194:197], v189 offset:20480
	ds_read_b128 v[198:201], v189 offset:21504
	ds_read_b128 v[202:205], v189 offset:22528
	ds_read_b128 v[206:209], v189 offset:23552
	global_load_lds_dwordx4 v[184:185], off
	s_add_i32 m0, s8, 0x2000
	s_add_u32 s8, s26, 0xb0000
	v_lshl_add_u64 v[210:211], s[26:27], 0, v[162:163]
	s_addc_u32 s9, s27, 0
	s_add_i32 s52, s53, s36
	global_load_lds_dwordx4 v[210:211], off
	v_lshl_add_u64 v[212:213], s[8:9], 0, v[0:1]
	s_mov_b32 m0, s52
	v_lshl_add_u64 v[214:215], s[28:29], 0, v[160:161]
	global_load_lds_dwordx4 v[212:213], off
	v_lshl_add_u64 v[212:213], s[8:9], 0, v[162:163]
	s_add_i32 m0, s52, 0x2000
	s_nop 0
	global_load_lds_dwordx4 v[212:213], off
	v_lshl_add_u64 v[212:213], s[28:29], 0, v[158:159]
	s_mov_b32 m0, s37
	s_nop 0
	global_load_lds_dwordx4 v[212:213], off
	s_mov_b32 m0, s38
	s_nop 0
	global_load_lds_dwordx4 v[214:215], off
	s_waitcnt vmcnt(8)
	s_waitcnt lgkmcnt(0)
	s_setprio 1
	s_barrier
; #define PG8_STAGE(bufoff, gbase, voff) do { _Pragma("unroll") for (int _i = 0; _i < 2; ++_i) \
;         __builtin_amdgcn_global_load_lds((const unsigned*)((const char*)(gbase) + (voff)[_i]), (PG8_LAS unsigned*)(lds + (bufoff) + ldsw + _i * 8192), 16, 0, 0); } while (0)
; #define PG8_LDA(dst, b, h) do { _Pragma("unroll") for (int m = 0; m < 4; ++m) _Pragma("unroll") for (int k = 0; k < 2; ++k) dst[m][k] = *(const PG8_LAS bf16x8*)(lds + PG8_SA(b, h) + aoff + m * 2048 + k * 1024); } while (0)
; #define PG8_LDB(dst, b, h) do { _Pragma("unroll") for (int n = 0; n < 2; ++n) _Pragma("unroll") for (int k = 0; k < 2; ++k) dst[n][k] = *(const PG8_LAS bf16x8*)(lds + PG8_SB(b, h) + boff + n * 2048 + k * 1024); } while (0)
; #define PG8_MMA(ai, bj, At, Bt) do { __builtin_amdgcn_s_setprio(1); _Pragma("unroll") for (int m = 0; m < 4; ++m) _Pragma("unroll") for (int n = 0; n < 2; ++n) _Pragma("unroll") for (int k = 0; k < 2; ++k) \
;         acc[ai][bj][m][n] = __builtin_amdgcn_mfma_f32_16x16x32_bf16(Bt[n][k], At[m][k], acc[ai][bj][m][n], 0, 0, 0); __builtin_amdgcn_s_setprio(0); } while (0)
; #define PG8_WAIT_V(n) asm volatile("s_waitcnt vmcnt(" #n ")" ::: "memory")
; #define PG8_WAIT_L(n) asm volatile("s_waitcnt lgkmcnt(" #n ")" ::: "memory")
; #define PG8_BAR __builtin_amdgcn_s_barrier()
; #define PG8_SCHED __builtin_amdgcn_sched_barrier(0)
; template <class Epi, class Sched, bool ALIGN_EPI = false, bool SP2 = false>
; __device__ __forceinline__ void gemm_phase(PG8_LAS unsigned char* lds, const Gemm g, const Sched& S, const Epi& E, const int wv) {
;     ...
;             PG8_WAIT_V(8); PG8_WAIT_L(0); PG8_BAR; PG8_MMA(1, 0, At, B0); PG8_MMA(1, 1, At, B1); PG8_BAR; PG8_SCHED;
;             PG8_LDB(B0, 1, 0); PG8_LDB(B1, 1, 1); PG8_SCHED; PG8_LDA(At, 1, 0); PG8_STAGE(PG8_SA(0, 1), a2 + hstep, voffA);
;             PG8_WAIT_V(8); PG8_WAIT_L(0); PG8_BAR; PG8_MMA(0, 0, At, B0); PG8_MMA(0, 1, At, B1); PG8_BAR; PG8_SCHED;
	s_waitcnt lgkmcnt(0)
	v_mfma_f32_16x16x32_bf16 v[62:65], v[122:125], v[172:175], v[62:65]
	v_mfma_f32_16x16x32_bf16 v[58:61], v[138:141], v[172:175], v[58:61]
	v_mfma_f32_16x16x32_bf16 v[46:49], v[122:125], v[180:183], v[46:49]
	v_mfma_f32_16x16x32_bf16 v[42:45], v[138:141], v[180:183], v[42:45]
	v_mfma_f32_16x16x32_bf16 v[30:33], v[122:125], v[194:197], v[30:33]
	v_mfma_f32_16x16x32_bf16 v[26:29], v[138:141], v[194:197], v[26:29]
	v_mfma_f32_16x16x32_bf16 v[14:17], v[122:125], v[202:205], v[14:17]
	v_mfma_f32_16x16x32_bf16 v[10:13], v[138:141], v[202:205], v[10:13]
	v_mfma_f32_16x16x32_bf16 v[62:65], v[130:133], v[176:179], v[62:65]
	v_mfma_f32_16x16x32_bf16 v[58:61], v[142:145], v[176:179], v[58:61]
	v_mfma_f32_16x16x32_bf16 v[46:49], v[130:133], v[190:193], v[46:49]
	v_mfma_f32_16x16x32_bf16 v[42:45], v[142:145], v[190:193], v[42:45]
	v_mfma_f32_16x16x32_bf16 v[30:33], v[130:133], v[198:201], v[30:33]
	v_mfma_f32_16x16x32_bf16 v[26:29], v[142:145], v[198:201], v[26:29]
	v_mfma_f32_16x16x32_bf16 v[14:17], v[130:133], v[206:209], v[14:17]
	v_mfma_f32_16x16x32_bf16 v[10:13], v[142:145], v[206:209], v[10:13]
	s_setprio 0
	s_setprio 1
	v_mfma_f32_16x16x32_bf16 v[54:57], v[146:149], v[172:175], v[54:57]
	v_mfma_f32_16x16x32_bf16 v[50:53], v[154:157], v[172:175], v[50:53]
	v_mfma_f32_16x16x32_bf16 v[38:41], v[146:149], v[180:183], v[38:41]
	v_mfma_f32_16x16x32_bf16 v[34:37], v[154:157], v[180:183], v[34:37]
	v_mfma_f32_16x16x32_bf16 v[22:25], v[146:149], v[194:197], v[22:25]
	v_mfma_f32_16x16x32_bf16 v[18:21], v[154:157], v[194:197], v[18:21]
	v_mfma_f32_16x16x32_bf16 v[6:9], v[146:149], v[202:205], v[6:9]
	v_mfma_f32_16x16x32_bf16 v[2:5], v[154:157], v[202:205], v[2:5]
	v_mfma_f32_16x16x32_bf16 v[54:57], v[150:153], v[176:179], v[54:57]
	v_mfma_f32_16x16x32_bf16 v[50:53], v[168:171], v[176:179], v[50:53]
	v_mfma_f32_16x16x32_bf16 v[38:41], v[150:153], v[190:193], v[38:41]
	v_mfma_f32_16x16x32_bf16 v[34:37], v[168:171], v[190:193], v[34:37]
	v_mfma_f32_16x16x32_bf16 v[22:25], v[150:153], v[198:201], v[22:25]
	v_mfma_f32_16x16x32_bf16 v[18:21], v[168:171], v[198:201], v[18:21]
	v_mfma_f32_16x16x32_bf16 v[6:9], v[150:153], v[206:209], v[6:9]
	v_mfma_f32_16x16x32_bf16 v[2:5], v[168:171], v[206:209], v[2:5]
	s_barrier
	s_setprio 0
	s_add_i32 s52, 0, 0x18000
	s_add_i32 s53, 0, 0x1c000
	v_add_u32_e32 v142, s52, v187
	v_add_u32_e32 v168, s53, v187
	ds_read_b128 v[122:125], v142
	ds_read_b128 v[130:133], v142 offset:1024
	ds_read_b128 v[138:141], v142 offset:2048
	ds_read_b128 v[142:145], v142 offset:3072
	ds_read_b128 v[146:149], v168
	ds_read_b128 v[150:153], v168 offset:1024
	ds_read_b128 v[154:157], v168 offset:2048
	ds_read_b128 v[168:171], v168 offset:3072
	s_add_u32 s8, s28, 0xb0000
	s_addc_u32 s9, s29, 0
	s_mov_b32 m0, s39
	v_lshl_add_u64 v[216:217], s[8:9], 0, v[158:159]
	ds_read_b128 v[172:175], v189 offset:32768
	ds_read_b128 v[176:179], v189 offset:33792
	ds_read_b128 v[180:183], v189 offset:34816
	ds_read_b128 v[190:193], v189 offset:35840
	ds_read_b128 v[194:197], v189 offset:36864
	ds_read_b128 v[198:201], v189 offset:37888
	ds_read_b128 v[202:205], v189 offset:38912
	ds_read_b128 v[206:209], v189 offset:39936
	global_load_lds_dwordx4 v[216:217], off
	v_lshl_add_u64 v[216:217], s[8:9], 0, v[160:161]
	s_mov_b32 m0, s40
	s_nop 0
	global_load_lds_dwordx4 v[216:217], off
	s_waitcnt vmcnt(8)
	s_waitcnt lgkmcnt(0)
	s_setprio 1
	s_barrier
	s_waitcnt lgkmcnt(0)
	v_mfma_f32_16x16x32_bf16 v[134:137], v[122:125], v[172:175], v[134:137]
	v_mfma_f32_16x16x32_bf16 v[126:129], v[138:141], v[172:175], v[126:129]
	v_mfma_f32_16x16x32_bf16 v[110:113], v[122:125], v[180:183], v[110:113]
	v_mfma_f32_16x16x32_bf16 v[106:109], v[138:141], v[180:183], v[106:109]
	v_mfma_f32_16x16x32_bf16 v[94:97], v[122:125], v[194:197], v[94:97]
	v_mfma_f32_16x16x32_bf16 v[90:93], v[138:141], v[194:197], v[90:93]
	v_mfma_f32_16x16x32_bf16 v[78:81], v[122:125], v[202:205], v[78:81]
	v_mfma_f32_16x16x32_bf16 v[74:77], v[138:141], v[202:205], v[74:77]
	v_mfma_f32_16x16x32_bf16 v[134:137], v[130:133], v[176:179], v[134:137]
	v_mfma_f32_16x16x32_bf16 v[126:129], v[142:145], v[176:179], v[126:129]
	v_mfma_f32_16x16x32_bf16 v[110:113], v[130:133], v[190:193], v[110:113]
	v_mfma_f32_16x16x32_bf16 v[106:109], v[142:145], v[190:193], v[106:109]
	v_mfma_f32_16x16x32_bf16 v[94:97], v[130:133], v[198:201], v[94:97]
	v_mfma_f32_16x16x32_bf16 v[90:93], v[142:145], v[198:201], v[90:93]
	v_mfma_f32_16x16x32_bf16 v[78:81], v[130:133], v[206:209], v[78:81]
	v_mfma_f32_16x16x32_bf16 v[74:77], v[142:145], v[206:209], v[74:77]
	s_setprio 0
	s_setprio 1
	v_mfma_f32_16x16x32_bf16 v[118:121], v[146:149], v[172:175], v[118:121]
	v_mfma_f32_16x16x32_bf16 v[114:117], v[154:157], v[172:175], v[114:117]
	v_mfma_f32_16x16x32_bf16 v[102:105], v[146:149], v[180:183], v[102:105]
	v_mfma_f32_16x16x32_bf16 v[98:101], v[154:157], v[180:183], v[98:101]
	v_mfma_f32_16x16x32_bf16 v[86:89], v[146:149], v[194:197], v[86:89]
	v_mfma_f32_16x16x32_bf16 v[82:85], v[154:157], v[194:197], v[82:85]
	v_mfma_f32_16x16x32_bf16 v[70:73], v[146:149], v[202:205], v[70:73]
	v_mfma_f32_16x16x32_bf16 v[66:69], v[154:157], v[202:205], v[66:69]
	v_mfma_f32_16x16x32_bf16 v[118:121], v[150:153], v[176:179], v[118:121]
	v_mfma_f32_16x16x32_bf16 v[114:117], v[168:171], v[176:179], v[114:117]
	v_mfma_f32_16x16x32_bf16 v[102:105], v[150:153], v[190:193], v[102:105]
	v_mfma_f32_16x16x32_bf16 v[98:101], v[168:171], v[190:193], v[98:101]
	v_mfma_f32_16x16x32_bf16 v[86:89], v[150:153], v[198:201], v[86:89]
	v_mfma_f32_16x16x32_bf16 v[82:85], v[168:171], v[198:201], v[82:85]
	v_mfma_f32_16x16x32_bf16 v[70:73], v[150:153], v[206:209], v[70:73]
	v_mfma_f32_16x16x32_bf16 v[66:69], v[168:171], v[206:209], v[66:69]
	s_barrier
; #define PG8_STAGE(bufoff, gbase, voff) do { _Pragma("unroll") for (int _i = 0; _i < 2; ++_i) \
;         __builtin_amdgcn_global_load_lds((const unsigned*)((const char*)(gbase) + (voff)[_i]), (PG8_LAS unsigned*)(lds + (bufoff) + ldsw + _i * 8192), 16, 0, 0); } while (0)
; #define PG8_LDA(dst, b, h) do { _Pragma("unroll") for (int m = 0; m < 4; ++m) _Pragma("unroll") for (int k = 0; k < 2; ++k) dst[m][k] = *(const PG8_LAS bf16x8*)(lds + PG8_SA(b, h) + aoff + m * 2048 + k * 1024); } while (0)
; #define PG8_MMA(ai, bj, At, Bt) do { __builtin_amdgcn_s_setprio(1); _Pragma("unroll") for (int m = 0; m < 4; ++m) _Pragma("unroll") for (int n = 0; n < 2; ++n) _Pragma("unroll") for (int k = 0; k < 2; ++k) \
;         acc[ai][bj][m][n] = __builtin_amdgcn_mfma_f32_16x16x32_bf16(Bt[n][k], At[m][k], acc[ai][bj][m][n], 0, 0, 0); __builtin_amdgcn_s_setprio(0); } while (0)
; #define PG8_WAIT_V(n) asm volatile("s_waitcnt vmcnt(" #n ")" ::: "memory")
; #define PG8_WAIT_L(n) asm volatile("s_waitcnt lgkmcnt(" #n ")" ::: "memory")
; #define PG8_BAR __builtin_amdgcn_s_barrier()
; #define PG8_SCHED __builtin_amdgcn_sched_barrier(0)
; template <class Epi, class Sched, bool ALIGN_EPI = false, bool SP2 = false>
; __device__ __forceinline__ void gemm_phase(PG8_LAS unsigned char* lds, const Gemm g, const Sched& S, const Epi& E, const int wv) {
;     ...
;             PG8_LDA(At, 1, 1); PG8_STAGE(PG8_SB(1, 0), b3, voffB); PG8_STAGE(PG8_SB(1, 1), b3 + hstep, voffB); PG8_STAGE(PG8_SA(1, 0), a3, voffA);
;             PG8_WAIT_V(8); PG8_WAIT_L(0); PG8_BAR; PG8_MMA(1, 0, At, B0); PG8_MMA(1, 1, At, B1); PG8_BAR; PG8_SCHED;
;     ...
;         if constexpr (ALIGN_EPI) { if (wr == 0) PG8_BAR; }
	s_setprio 0
	s_add_i32 s8, s52, s36
	v_lshl_add_u64 v[184:185], v[184:185], 0, s[2:3]
	s_mov_b32 m0, s8
	ds_read_b128 v[172:175], v189 offset:49152
	ds_read_b128 v[176:179], v189 offset:50176
	ds_read_b128 v[180:183], v189 offset:51200
	ds_read_b128 v[190:193], v189 offset:52224
	ds_read_b128 v[194:197], v189 offset:53248
	ds_read_b128 v[198:201], v189 offset:54272
	ds_read_b128 v[202:205], v189 offset:55296
	ds_read_b128 v[206:209], v189 offset:56320
	global_load_lds_dwordx4 v[184:185], off
	s_add_i32 m0, s8, 0x2000
	s_add_u32 s8, s26, 0xb0080
	v_lshl_add_u64 v[184:185], v[210:211], 0, s[2:3]
	s_addc_u32 s9, s27, 0
	s_add_i32 s26, s53, s36
	global_load_lds_dwordx4 v[184:185], off
	v_lshl_add_u64 v[184:185], s[8:9], 0, v[0:1]
	s_mov_b32 m0, s26
	s_nop 0
	global_load_lds_dwordx4 v[184:185], off
	v_lshl_add_u64 v[184:185], s[8:9], 0, v[162:163]
	s_add_i32 m0, s26, 0x2000
	s_nop 0
	global_load_lds_dwordx4 v[184:185], off
	v_lshl_add_u64 v[184:185], v[212:213], 0, s[2:3]
	s_mov_b32 m0, s42
	s_nop 0
	global_load_lds_dwordx4 v[184:185], off
	v_lshl_add_u64 v[184:185], v[214:215], 0, s[2:3]
	s_mov_b32 m0, s43
	s_nop 0
	global_load_lds_dwordx4 v[184:185], off
	s_waitcnt vmcnt(8)
	s_waitcnt lgkmcnt(0)
	s_setprio 1
	s_barrier
	s_waitcnt lgkmcnt(0)
	v_mfma_f32_16x16x32_bf16 v[62:65], v[122:125], v[172:175], v[62:65]
	v_mfma_f32_16x16x32_bf16 v[58:61], v[138:141], v[172:175], v[58:61]
	v_mfma_f32_16x16x32_bf16 v[46:49], v[122:125], v[180:183], v[46:49]
	v_mfma_f32_16x16x32_bf16 v[42:45], v[138:141], v[180:183], v[42:45]
	v_mfma_f32_16x16x32_bf16 v[30:33], v[122:125], v[194:197], v[30:33]
	v_mfma_f32_16x16x32_bf16 v[26:29], v[138:141], v[194:197], v[26:29]
	v_mfma_f32_16x16x32_bf16 v[14:17], v[122:125], v[202:205], v[14:17]
	v_mfma_f32_16x16x32_bf16 v[10:13], v[138:141], v[202:205], v[10:13]
	v_mfma_f32_16x16x32_bf16 v[62:65], v[130:133], v[176:179], v[62:65]
	v_mfma_f32_16x16x32_bf16 v[58:61], v[142:145], v[176:179], v[58:61]
	v_mfma_f32_16x16x32_bf16 v[46:49], v[130:133], v[190:193], v[46:49]
	v_mfma_f32_16x16x32_bf16 v[42:45], v[142:145], v[190:193], v[42:45]
	v_mfma_f32_16x16x32_bf16 v[30:33], v[130:133], v[198:201], v[30:33]
	v_mfma_f32_16x16x32_bf16 v[26:29], v[142:145], v[198:201], v[26:29]
	v_mfma_f32_16x16x32_bf16 v[14:17], v[130:133], v[206:209], v[14:17]
	v_mfma_f32_16x16x32_bf16 v[10:13], v[142:145], v[206:209], v[10:13]
	s_setprio 0
	s_setprio 1
	v_mfma_f32_16x16x32_bf16 v[54:57], v[146:149], v[172:175], v[54:57]
	v_mfma_f32_16x16x32_bf16 v[50:53], v[154:157], v[172:175], v[50:53]
	v_mfma_f32_16x16x32_bf16 v[38:41], v[146:149], v[180:183], v[38:41]
	v_mfma_f32_16x16x32_bf16 v[34:37], v[154:157], v[180:183], v[34:37]
	v_mfma_f32_16x16x32_bf16 v[22:25], v[146:149], v[194:197], v[22:25]
	v_mfma_f32_16x16x32_bf16 v[18:21], v[154:157], v[194:197], v[18:21]
	v_mfma_f32_16x16x32_bf16 v[6:9], v[146:149], v[202:205], v[6:9]
	v_mfma_f32_16x16x32_bf16 v[2:5], v[154:157], v[202:205], v[2:5]
	v_mfma_f32_16x16x32_bf16 v[54:57], v[150:153], v[176:179], v[54:57]
	v_mfma_f32_16x16x32_bf16 v[50:53], v[168:171], v[176:179], v[50:53]
	v_mfma_f32_16x16x32_bf16 v[38:41], v[150:153], v[190:193], v[38:41]
	v_mfma_f32_16x16x32_bf16 v[34:37], v[168:171], v[190:193], v[34:37]
	v_mfma_f32_16x16x32_bf16 v[22:25], v[150:153], v[198:201], v[22:25]
	v_mfma_f32_16x16x32_bf16 v[18:21], v[168:171], v[198:201], v[18:21]
	v_mfma_f32_16x16x32_bf16 v[6:9], v[150:153], v[206:209], v[6:9]
	v_mfma_f32_16x16x32_bf16 v[2:5], v[168:171], v[206:209], v[2:5]
	s_barrier
	s_setprio 0
	s_add_i32 s51, s51, 2
	s_add_u32 s49, s49, 0x100
	s_addc_u32 s50, s50, 0
	s_cmp_gt_u32 s51, 41
	s_mov_b64 s[8:9], s[10:11]
	s_cbranch_scc0 .LBB0_504
	s_and_b64 vcc, exec, s[18:19]
	s_cbranch_vccz .LBB0_507
	s_barrier
